# version 63 plus first K-iteration of the three GEMM loops peeled (first MFMA per accumulator takes srcC=0, no 128-register zeroing per unit), all MFMA blocks 8-byte aligned
# speedup vs baseline: 1.0141x; 1.0141x over previous
; #define PG8_STAGE(bufoff, gbase, voff) do { _Pragma("unroll") for (int _i = 0; _i < 2; ++_i) \
;         __builtin_amdgcn_global_load_lds((const unsigned*)((const char*)(gbase) + (voff)[_i]), (PG8_LAS unsigned*)(lds + (bufoff) + ldsw + _i * 8192), 16, 0, 0); } while (0)
; #define PG8_LDA(dst, b, h) do { _Pragma("unroll") for (int m = 0; m < 4; ++m) _Pragma("unroll") for (int k = 0; k < 2; ++k) dst[m][k] = *(const PG8_LAS bf16x8*)(lds + PG8_SA(b, h) + aoff + m * 2048 + k * 1024); } while (0)
; #define PG8_LDB(dst, b, h) do { _Pragma("unroll") for (int n = 0; n < 2; ++n) _Pragma("unroll") for (int k = 0; k < 2; ++k) dst[n][k] = *(const PG8_LAS bf16x8*)(lds + PG8_SB(b, h) + boff + n * 2048 + k * 1024); } while (0)
; #define PG8_WAIT_V(n) asm volatile("s_waitcnt vmcnt(" #n ")" ::: "memory")
; #define PG8_WAIT_L(n) asm volatile("s_waitcnt lgkmcnt(" #n ")" ::: "memory")
; #define PG8_BAR __builtin_amdgcn_s_barrier()
; #define PG8_SCHED __builtin_amdgcn_sched_barrier(0)
; template <class Epi, class Sched, bool ALIGN_EPI = false, bool SP2 = false>
; __device__ __forceinline__ void gemm_phase(PG8_LAS unsigned char* lds, const Gemm g, const Sched& S, const Epi& E, const int tid_in) {
;     ...
;         const bool has_next = S.next(ui + 1, nxt);
;         const char* nA = has_next ? (const char*)g.A + (size_t)nxt.pm * tstep : cA; const char* nB = has_next ? (const char*)g.Bt + (size_t)nxt.pn * tstep : cB;
;         for (int t = 0; t < nt; t += 2) {
;             const bool last = (t == nt - 2);
;             const char* a1 = cA + (size_t)(t + 1) * kstep;
;             const char* a2 = last ? nA : cA + (size_t)(t + 2) * kstep; const char* b2 = last ? nB : cB + (size_t)(t + 2) * kstep;
;             const char* a3 = a2 + kstep; const char* b3 = b2 + kstep;
;             if (last && has_next) S.a_ready(nxt);
;             if constexpr (SP2) {
;             PG8_LDB(B0, 0, 0); PG8_LDB(B1, 0, 1); PG8_SCHED; PG8_LDA(At, 0, 0); PG8_STAGE(PG8_SA(1, 1), a1 + hstep, voffA);
;             PG8_WAIT_V(8); PG8_WAIT_L(0); PG8_BAR; PG8_MMA(0, 0, At, B0); PG8_MMA(0, 1, At, B1); PG8_BAR; PG8_SCHED;
;             PG8_LDA(At, 0, 1); PG8_STAGE(PG8_SB(0, 0), b2, voffB); PG8_STAGE(PG8_SB(0, 1), b2 + hstep, voffB); PG8_STAGE(PG8_SA(0, 0), a2, voffA);
;             PG8_WAIT_V(8); PG8_WAIT_L(0); PG8_BAR; PG8_MMA(1, 0, At, B0); PG8_MMA(1, 1, At, B1); PG8_BAR; PG8_SCHED;
.LBB0_92:
	s_ashr_i32 s25, s24, 31
	s_lshl_b64 s[16:17], s[24:25], 19
	s_add_u32 s34, s84, s16
	s_addc_u32 s35, s85, s17
	s_and_b64 s[16:17], s[36:37], exec
	s_cselect_b32 s11, s35, s15
	s_cselect_b32 s16, s34, s14
	s_ashr_i32 s21, s20, 31
	s_lshl_b64 s[40:41], s[20:21], 19
	s_add_u32 s40, s3, s40
	s_addc_u32 s41, s18, s41
	s_and_b64 s[42:43], s[36:37], exec
	s_cselect_b32 s17, s41, s13
	s_cselect_b32 s21, s40, s12
	s_add_u32 s42, s14, 0x40080
	s_addc_u32 s43, s15, 0
	s_add_u32 s25, s12, 0x100
	s_addc_u32 s39, s13, 0
	s_mov_b32 s45, -2
	s_add_u32 s12, s42, 0xfffc0080
	s_addc_u32 s13, s43, -1
	s_add_i32 s46, 0, 0x10000
	s_cmp_eq_u32 s45, 12
	s_cselect_b32 s15, s11, s13
	s_cselect_b32 s14, s16, s12
	v_add_u32_e32 v148, s46, v150
	s_cselect_b32 s13, s17, s39
	s_cselect_b32 s12, s21, s25
	s_add_i32 s48, 0, 0x14000
	ds_read_b128 v[144:147], v148
	ds_read_b128 v[154:157], v148 offset:1024
	ds_read_b128 v[158:161], v148 offset:2048
	ds_read_b128 v[162:165], v148 offset:3072
	v_add_u32_e32 v148, s48, v150
	ds_read_b128 v[166:169], v148
	ds_read_b128 v[170:173], v148 offset:1024
	ds_read_b128 v[174:177], v148 offset:2048
	ds_read_b128 v[178:181], v148 offset:3072
	v_lshl_add_u64 v[148:149], s[42:43], 0, v[140:141]
	s_add_i32 m0, s22, 0xc000
	ds_read_b128 v[182:185], v152
	ds_read_b128 v[186:189], v152 offset:1024
	ds_read_b128 v[190:193], v152 offset:2048
	ds_read_b128 v[198:201], v152 offset:3072
	ds_read_b128 v[202:205], v152 offset:4096
	ds_read_b128 v[206:209], v152 offset:5120
	ds_read_b128 v[210:213], v152 offset:6144
	ds_read_b128 v[214:217], v152 offset:7168
	global_load_lds_dwordx4 v[148:149], off
	v_lshl_add_u64 v[148:149], s[42:43], 0, v[142:143]
	s_add_i32 m0, s22, 0xe000
	s_nop 0
	global_load_lds_dwordx4 v[148:149], off
	s_nop 0
	s_waitcnt vmcnt(8)
	s_waitcnt lgkmcnt(0)
	s_barrier
	v_mfma_f32_16x16x32_bf16 v[130:133], v[144:147], v[182:185], 0
	v_mfma_f32_16x16x32_bf16 v[130:133], v[154:157], v[186:189], v[130:133]
	v_mfma_f32_16x16x32_bf16 v[114:117], v[144:147], v[190:193], 0
	v_mfma_f32_16x16x32_bf16 v[114:117], v[154:157], v[198:201], v[114:117]
	v_mfma_f32_16x16x32_bf16 v[98:101], v[144:147], v[202:205], 0
	v_mfma_f32_16x16x32_bf16 v[98:101], v[154:157], v[206:209], v[98:101]
	v_mfma_f32_16x16x32_bf16 v[82:85], v[144:147], v[210:213], 0
	v_mfma_f32_16x16x32_bf16 v[82:85], v[154:157], v[214:217], v[82:85]
	v_mfma_f32_16x16x32_bf16 v[126:129], v[158:161], v[182:185], 0
	v_mfma_f32_16x16x32_bf16 v[126:129], v[162:165], v[186:189], v[126:129]
	v_mfma_f32_16x16x32_bf16 v[110:113], v[158:161], v[190:193], 0
	v_mfma_f32_16x16x32_bf16 v[110:113], v[162:165], v[198:201], v[110:113]
	v_mfma_f32_16x16x32_bf16 v[94:97], v[158:161], v[202:205], 0
	v_mfma_f32_16x16x32_bf16 v[94:97], v[162:165], v[206:209], v[94:97]
	v_mfma_f32_16x16x32_bf16 v[78:81], v[158:161], v[210:213], 0
	v_mfma_f32_16x16x32_bf16 v[78:81], v[162:165], v[214:217], v[78:81]
	v_mfma_f32_16x16x32_bf16 v[122:125], v[166:169], v[182:185], 0
	v_mfma_f32_16x16x32_bf16 v[122:125], v[170:173], v[186:189], v[122:125]
	v_mfma_f32_16x16x32_bf16 v[106:109], v[166:169], v[190:193], 0
	v_mfma_f32_16x16x32_bf16 v[106:109], v[170:173], v[198:201], v[106:109]
	v_mfma_f32_16x16x32_bf16 v[90:93], v[166:169], v[202:205], 0
	v_mfma_f32_16x16x32_bf16 v[90:93], v[170:173], v[206:209], v[90:93]
	v_mfma_f32_16x16x32_bf16 v[74:77], v[166:169], v[210:213], 0
	v_mfma_f32_16x16x32_bf16 v[74:77], v[170:173], v[214:217], v[74:77]
	v_mfma_f32_16x16x32_bf16 v[118:121], v[174:177], v[182:185], 0
	v_mfma_f32_16x16x32_bf16 v[118:121], v[178:181], v[186:189], v[118:121]
	v_mfma_f32_16x16x32_bf16 v[102:105], v[174:177], v[190:193], 0
	v_mfma_f32_16x16x32_bf16 v[102:105], v[178:181], v[198:201], v[102:105]
	v_mfma_f32_16x16x32_bf16 v[86:89], v[174:177], v[202:205], 0
	v_mfma_f32_16x16x32_bf16 v[86:89], v[178:181], v[206:209], v[86:89]
	v_mfma_f32_16x16x32_bf16 v[70:73], v[174:177], v[210:213], 0
	v_mfma_f32_16x16x32_bf16 v[70:73], v[178:181], v[214:217], v[70:73]
	s_barrier
	s_add_i32 s46, s46, s19
	v_lshl_add_u64 v[148:149], s[12:13], 0, v[134:135]
	s_mov_b32 m0, s46
	ds_read_b128 v[182:185], v152 offset:16384
	ds_read_b128 v[186:189], v152 offset:17408
	ds_read_b128 v[190:193], v152 offset:18432
	ds_read_b128 v[198:201], v152 offset:19456
	ds_read_b128 v[202:205], v152 offset:20480
	ds_read_b128 v[206:209], v152 offset:21504
	ds_read_b128 v[210:213], v152 offset:22528
	ds_read_b128 v[214:217], v152 offset:23552
	global_load_lds_dwordx4 v[148:149], off
	s_add_i32 m0, s46, 0x2000
	s_add_u32 s46, s12, 0x40000
	v_lshl_add_u64 v[218:219], s[12:13], 0, v[138:139]
	s_addc_u32 s47, s13, 0
	s_add_i32 s48, s48, s19
	global_load_lds_dwordx4 v[218:219], off
	v_lshl_add_u64 v[220:221], s[46:47], 0, v[134:135]
	s_mov_b32 m0, s48
	v_lshl_add_u64 v[222:223], s[14:15], 0, v[136:137]
	global_load_lds_dwordx4 v[220:221], off
	v_lshl_add_u64 v[220:221], s[46:47], 0, v[138:139]
	s_add_i32 m0, s48, 0x2000
	s_nop 0
	global_load_lds_dwordx4 v[220:221], off
	v_lshl_add_u64 v[220:221], s[14:15], 0, v[2:3]
	s_mov_b32 m0, s22
	s_nop 0
	global_load_lds_dwordx4 v[220:221], off
	s_mov_b32 m0, s23
	s_nop 0
	global_load_lds_dwordx4 v[222:223], off
	s_waitcnt vmcnt(8)
	s_waitcnt lgkmcnt(0)
	s_barrier
; #define PG8_STAGE(bufoff, gbase, voff) do { _Pragma("unroll") for (int _i = 0; _i < 2; ++_i) \
;         __builtin_amdgcn_global_load_lds((const unsigned*)((const char*)(gbase) + (voff)[_i]), (PG8_LAS unsigned*)(lds + (bufoff) + ldsw + _i * 8192), 16, 0, 0); } while (0)
; #define PG8_LDA(dst, b, h) do { _Pragma("unroll") for (int m = 0; m < 4; ++m) _Pragma("unroll") for (int k = 0; k < 2; ++k) dst[m][k] = *(const PG8_LAS bf16x8*)(lds + PG8_SA(b, h) + aoff + m * 2048 + k * 1024); } while (0)
; #define PG8_LDB(dst, b, h) do { _Pragma("unroll") for (int n = 0; n < 2; ++n) _Pragma("unroll") for (int k = 0; k < 2; ++k) dst[n][k] = *(const PG8_LAS bf16x8*)(lds + PG8_SB(b, h) + boff + n * 2048 + k * 1024); } while (0)
; #define PG8_MMA(ai, bj, At, Bt) do { __builtin_amdgcn_s_setprio(1); _Pragma("unroll") for (int m = 0; m < 4; ++m) _Pragma("unroll") for (int n = 0; n < 2; ++n) _Pragma("unroll") for (int k = 0; k < 2; ++k) \
;         acc[ai][bj][m][n] = __builtin_amdgcn_mfma_f32_16x16x32_bf16(Bt[n][k], At[m][k], acc[ai][bj][m][n], 0, 0, 0); __builtin_amdgcn_s_setprio(0); } while (0)
; #define PG8_WAIT_V(n) asm volatile("s_waitcnt vmcnt(" #n ")" ::: "memory")
; #define PG8_WAIT_L(n) asm volatile("s_waitcnt lgkmcnt(" #n ")" ::: "memory")
; #define PG8_BAR __builtin_amdgcn_s_barrier()
; #define PG8_SCHED __builtin_amdgcn_sched_barrier(0)
; template <class Epi, class Sched, bool ALIGN_EPI = false, bool SP2 = false>
; __device__ __forceinline__ void gemm_phase(PG8_LAS unsigned char* lds, const Gemm g, const Sched& S, const Epi& E, const int tid_in) {
;     ...
;             PG8_WAIT_V(8); PG8_WAIT_L(0); PG8_BAR; PG8_MMA(1, 0, At, B0); PG8_MMA(1, 1, At, B1); PG8_BAR; PG8_SCHED;
;             PG8_LDB(B0, 1, 0); PG8_LDB(B1, 1, 1); PG8_SCHED; PG8_LDA(At, 1, 0); PG8_STAGE(PG8_SA(0, 1), a2 + hstep, voffA);
;             PG8_WAIT_V(8); PG8_WAIT_L(0); PG8_BAR; PG8_MMA(0, 0, At, B0); PG8_MMA(0, 1, At, B1); PG8_BAR; PG8_SCHED;
	v_mfma_f32_16x16x32_bf16 v[66:69], v[144:147], v[182:185], 0
	v_mfma_f32_16x16x32_bf16 v[66:69], v[154:157], v[186:189], v[66:69]
	v_mfma_f32_16x16x32_bf16 v[50:53], v[144:147], v[190:193], 0
	v_mfma_f32_16x16x32_bf16 v[50:53], v[154:157], v[198:201], v[50:53]
	v_mfma_f32_16x16x32_bf16 v[34:37], v[144:147], v[202:205], 0
	v_mfma_f32_16x16x32_bf16 v[34:37], v[154:157], v[206:209], v[34:37]
	v_mfma_f32_16x16x32_bf16 v[18:21], v[144:147], v[210:213], 0
	v_mfma_f32_16x16x32_bf16 v[18:21], v[154:157], v[214:217], v[18:21]
	v_mfma_f32_16x16x32_bf16 v[62:65], v[158:161], v[182:185], 0
	v_mfma_f32_16x16x32_bf16 v[62:65], v[162:165], v[186:189], v[62:65]
	v_mfma_f32_16x16x32_bf16 v[46:49], v[158:161], v[190:193], 0
	v_mfma_f32_16x16x32_bf16 v[46:49], v[162:165], v[198:201], v[46:49]
	v_mfma_f32_16x16x32_bf16 v[30:33], v[158:161], v[202:205], 0
	v_mfma_f32_16x16x32_bf16 v[30:33], v[162:165], v[206:209], v[30:33]
	v_mfma_f32_16x16x32_bf16 v[14:17], v[158:161], v[210:213], 0
	v_mfma_f32_16x16x32_bf16 v[14:17], v[162:165], v[214:217], v[14:17]
	v_mfma_f32_16x16x32_bf16 v[58:61], v[166:169], v[182:185], 0
	v_mfma_f32_16x16x32_bf16 v[58:61], v[170:173], v[186:189], v[58:61]
	v_mfma_f32_16x16x32_bf16 v[42:45], v[166:169], v[190:193], 0
	v_mfma_f32_16x16x32_bf16 v[42:45], v[170:173], v[198:201], v[42:45]
	v_mfma_f32_16x16x32_bf16 v[26:29], v[166:169], v[202:205], 0
	v_mfma_f32_16x16x32_bf16 v[26:29], v[170:173], v[206:209], v[26:29]
	v_mfma_f32_16x16x32_bf16 v[10:13], v[166:169], v[210:213], 0
	v_mfma_f32_16x16x32_bf16 v[10:13], v[170:173], v[214:217], v[10:13]
	v_mfma_f32_16x16x32_bf16 v[54:57], v[174:177], v[182:185], 0
	v_mfma_f32_16x16x32_bf16 v[54:57], v[178:181], v[186:189], v[54:57]
	v_mfma_f32_16x16x32_bf16 v[38:41], v[174:177], v[190:193], 0
	v_mfma_f32_16x16x32_bf16 v[38:41], v[178:181], v[198:201], v[38:41]
	v_mfma_f32_16x16x32_bf16 v[22:25], v[174:177], v[202:205], 0
	v_mfma_f32_16x16x32_bf16 v[22:25], v[178:181], v[206:209], v[22:25]
	v_mfma_f32_16x16x32_bf16 v[6:9], v[174:177], v[210:213], 0
	v_mfma_f32_16x16x32_bf16 v[6:9], v[178:181], v[214:217], v[6:9]
	s_barrier
	s_add_i32 s46, 0, 0x18000
	v_add_u32_e32 v153, s46, v150
	s_add_i32 s47, 0, 0x1c000
	ds_read_b128 v[144:147], v153
	ds_read_b128 v[154:157], v153 offset:1024
	ds_read_b128 v[158:161], v153 offset:2048
	ds_read_b128 v[162:165], v153 offset:3072
	v_add_u32_e32 v153, s47, v150
	ds_read_b128 v[166:169], v153
	ds_read_b128 v[170:173], v153 offset:1024
	ds_read_b128 v[174:177], v153 offset:2048
	ds_read_b128 v[178:181], v153 offset:3072
	s_add_u32 s14, s14, 0x40000
	s_addc_u32 s15, s15, 0
	s_mov_b32 m0, s26
	v_lshl_add_u64 v[224:225], s[14:15], 0, v[2:3]
	ds_read_b128 v[182:185], v152 offset:32768
	ds_read_b128 v[186:189], v152 offset:33792
	ds_read_b128 v[190:193], v152 offset:34816
	ds_read_b128 v[198:201], v152 offset:35840
	ds_read_b128 v[202:205], v152 offset:36864
	ds_read_b128 v[206:209], v152 offset:37888
	ds_read_b128 v[210:213], v152 offset:38912
	ds_read_b128 v[214:217], v152 offset:39936
	global_load_lds_dwordx4 v[224:225], off
	v_lshl_add_u64 v[224:225], s[14:15], 0, v[136:137]
	s_mov_b32 m0, s27
	s_nop 0
	global_load_lds_dwordx4 v[224:225], off
	s_waitcnt vmcnt(8)
	s_waitcnt lgkmcnt(0)
	s_barrier
; #define PG8_STAGE(bufoff, gbase, voff) do { _Pragma("unroll") for (int _i = 0; _i < 2; ++_i) \
;         __builtin_amdgcn_global_load_lds((const unsigned*)((const char*)(gbase) + (voff)[_i]), (PG8_LAS unsigned*)(lds + (bufoff) + ldsw + _i * 8192), 16, 0, 0); } while (0)
; #define PG8_LDA(dst, b, h) do { _Pragma("unroll") for (int m = 0; m < 4; ++m) _Pragma("unroll") for (int k = 0; k < 2; ++k) dst[m][k] = *(const PG8_LAS bf16x8*)(lds + PG8_SA(b, h) + aoff + m * 2048 + k * 1024); } while (0)
; #define PG8_MMA(ai, bj, At, Bt) do { __builtin_amdgcn_s_setprio(1); _Pragma("unroll") for (int m = 0; m < 4; ++m) _Pragma("unroll") for (int n = 0; n < 2; ++n) _Pragma("unroll") for (int k = 0; k < 2; ++k) \
;         acc[ai][bj][m][n] = __builtin_amdgcn_mfma_f32_16x16x32_bf16(Bt[n][k], At[m][k], acc[ai][bj][m][n], 0, 0, 0); __builtin_amdgcn_s_setprio(0); } while (0)
; #define PG8_WAIT_V(n) asm volatile("s_waitcnt vmcnt(" #n ")" ::: "memory")
; #define PG8_WAIT_L(n) asm volatile("s_waitcnt lgkmcnt(" #n ")" ::: "memory")
; #define PG8_BAR __builtin_amdgcn_s_barrier()
; #define PG8_SCHED __builtin_amdgcn_sched_barrier(0)
; template <class Epi, class Sched, bool ALIGN_EPI = false, bool SP2 = false>
; __device__ __forceinline__ void gemm_phase(PG8_LAS unsigned char* lds, const Gemm g, const Sched& S, const Epi& E, const int tid_in) {
;     ...
;             PG8_WAIT_V(8); PG8_WAIT_L(0); PG8_BAR; PG8_MMA(0, 0, At, B0); PG8_MMA(0, 1, At, B1); PG8_BAR; PG8_SCHED;
;             PG8_LDA(At, 1, 1); PG8_STAGE(PG8_SB(1, 0), b3, voffB); PG8_STAGE(PG8_SB(1, 1), b3 + hstep, voffB); PG8_STAGE(PG8_SA(1, 0), a3, voffA);
;     __device__ __forceinline__ void operator()(const f32x4 (&acc)[2][2][4][2], const Unit& u, int wr, int wc, int fr, int fq) const {
;     ...
;         for (int ai = 0; ai < 2; ++ai)
; #pragma unroll
;             for (int m = 0; m < 4; ++m) rs[ai][m] = rowss[row0 + ai * HALF + m * 16];
	v_mfma_f32_16x16x32_bf16 v[130:133], v[144:147], v[182:185], v[130:133]
	v_mfma_f32_16x16x32_bf16 v[130:133], v[154:157], v[186:189], v[130:133]
	v_mfma_f32_16x16x32_bf16 v[114:117], v[144:147], v[190:193], v[114:117]
	v_mfma_f32_16x16x32_bf16 v[114:117], v[154:157], v[198:201], v[114:117]
	v_mfma_f32_16x16x32_bf16 v[98:101], v[144:147], v[202:205], v[98:101]
	v_mfma_f32_16x16x32_bf16 v[98:101], v[154:157], v[206:209], v[98:101]
	v_mfma_f32_16x16x32_bf16 v[82:85], v[144:147], v[210:213], v[82:85]
	v_mfma_f32_16x16x32_bf16 v[82:85], v[154:157], v[214:217], v[82:85]
	v_mfma_f32_16x16x32_bf16 v[126:129], v[158:161], v[182:185], v[126:129]
	v_mfma_f32_16x16x32_bf16 v[126:129], v[162:165], v[186:189], v[126:129]
	v_mfma_f32_16x16x32_bf16 v[110:113], v[158:161], v[190:193], v[110:113]
	v_mfma_f32_16x16x32_bf16 v[110:113], v[162:165], v[198:201], v[110:113]
	v_mfma_f32_16x16x32_bf16 v[94:97], v[158:161], v[202:205], v[94:97]
	v_mfma_f32_16x16x32_bf16 v[94:97], v[162:165], v[206:209], v[94:97]
	v_mfma_f32_16x16x32_bf16 v[78:81], v[158:161], v[210:213], v[78:81]
	v_mfma_f32_16x16x32_bf16 v[78:81], v[162:165], v[214:217], v[78:81]
	v_mfma_f32_16x16x32_bf16 v[122:125], v[166:169], v[182:185], v[122:125]
	v_mfma_f32_16x16x32_bf16 v[122:125], v[170:173], v[186:189], v[122:125]
	v_mfma_f32_16x16x32_bf16 v[106:109], v[166:169], v[190:193], v[106:109]
	v_mfma_f32_16x16x32_bf16 v[106:109], v[170:173], v[198:201], v[106:109]
	v_mfma_f32_16x16x32_bf16 v[90:93], v[166:169], v[202:205], v[90:93]
	v_mfma_f32_16x16x32_bf16 v[90:93], v[170:173], v[206:209], v[90:93]
	v_mfma_f32_16x16x32_bf16 v[74:77], v[166:169], v[210:213], v[74:77]
	v_mfma_f32_16x16x32_bf16 v[74:77], v[170:173], v[214:217], v[74:77]
	v_mfma_f32_16x16x32_bf16 v[118:121], v[174:177], v[182:185], v[118:121]
	v_mfma_f32_16x16x32_bf16 v[118:121], v[178:181], v[186:189], v[118:121]
	v_mfma_f32_16x16x32_bf16 v[102:105], v[174:177], v[190:193], v[102:105]
	v_mfma_f32_16x16x32_bf16 v[102:105], v[178:181], v[198:201], v[102:105]
	v_mfma_f32_16x16x32_bf16 v[86:89], v[174:177], v[202:205], v[86:89]
	v_mfma_f32_16x16x32_bf16 v[86:89], v[178:181], v[206:209], v[86:89]
	v_mfma_f32_16x16x32_bf16 v[70:73], v[174:177], v[210:213], v[70:73]
	v_mfma_f32_16x16x32_bf16 v[70:73], v[178:181], v[214:217], v[70:73]
	s_barrier
	s_add_i32 s14, s46, s19
	v_lshl_add_u64 v[148:149], v[148:149], 0, s[28:29]
	s_mov_b32 m0, s14
	ds_read_b128 v[182:185], v152 offset:49152
	ds_read_b128 v[186:189], v152 offset:50176
	ds_read_b128 v[190:193], v152 offset:51200
	ds_read_b128 v[198:201], v152 offset:52224
	ds_read_b128 v[202:205], v152 offset:53248
	ds_read_b128 v[206:209], v152 offset:54272
	ds_read_b128 v[210:213], v152 offset:55296
	ds_read_b128 v[214:217], v152 offset:56320
	global_load_lds_dwordx4 v[148:149], off
	s_add_i32 m0, s14, 0x2000
	s_add_u32 s12, s12, 0x40080
	v_lshl_add_u64 v[148:149], v[218:219], 0, s[28:29]
	s_addc_u32 s13, s13, 0
	s_add_i32 s14, s47, s19
	global_load_lds_dwordx4 v[148:149], off
	v_lshl_add_u64 v[148:149], s[12:13], 0, v[134:135]
	s_mov_b32 m0, s14
	s_nop 0
	global_load_lds_dwordx4 v[148:149], off
	v_lshl_add_u64 v[148:149], s[12:13], 0, v[138:139]
	s_add_i32 m0, s14, 0x2000
	s_nop 0
	global_load_lds_dwordx4 v[148:149], off
	v_lshl_add_u64 v[148:149], v[220:221], 0, s[28:29]
	s_mov_b32 m0, s30
	s_nop 0
	global_load_lds_dwordx4 v[148:149], off
	v_lshl_add_u64 v[148:149], v[222:223], 0, s[28:29]
	s_mov_b32 m0, s31
	s_nop 0
	global_load_lds_dwordx4 v[148:149], off
	s_waitcnt vmcnt(8)
	s_waitcnt lgkmcnt(0)
	s_cmp_lg_u32 s45, 12
	s_cbranch_scc1 .Lrs_in_skip_pin
	v_lshl_add_u32 v148, s38, 8, v5
	v_ashrrev_i32_e32 v149, 31, v148
	v_lshl_add_u64 v[148:149], v[148:149], 2, s[6:7]
	global_load_dword v226, v[148:149], off
	global_load_dword v227, v[148:149], off offset:64
	global_load_dword v228, v[148:149], off offset:128
	global_load_dword v229, v[148:149], off offset:192
	global_load_dword v238, v[148:149], off offset:512
	global_load_dword v239, v[148:149], off offset:576
	global_load_dword v240, v[148:149], off offset:640
	global_load_dword v241, v[148:149], off offset:704

; #define PG8_STAGE(bufoff, gbase, voff) do { _Pragma("unroll") for (int _i = 0; _i < 2; ++_i) \
;         __builtin_amdgcn_global_load_lds((const unsigned*)((const char*)(gbase) + (voff)[_i]), (PG8_LAS unsigned*)(lds + (bufoff) + ldsw + _i * 8192), 16, 0, 0); } while (0)
; #define PG8_LDA(dst, b, h) do { _Pragma("unroll") for (int m = 0; m < 4; ++m) _Pragma("unroll") for (int k = 0; k < 2; ++k) dst[m][k] = *(const PG8_LAS bf16x8*)(lds + PG8_SA(b, h) + aoff + m * 2048 + k * 1024); } while (0)
; #define PG8_LDB(dst, b, h) do { _Pragma("unroll") for (int n = 0; n < 2; ++n) _Pragma("unroll") for (int k = 0; k < 2; ++k) dst[n][k] = *(const PG8_LAS bf16x8*)(lds + PG8_SB(b, h) + boff + n * 2048 + k * 1024); } while (0)
; #define PG8_MMA(ai, bj, At, Bt) do { __builtin_amdgcn_s_setprio(1); _Pragma("unroll") for (int m = 0; m < 4; ++m) _Pragma("unroll") for (int n = 0; n < 2; ++n) _Pragma("unroll") for (int k = 0; k < 2; ++k) \
;         acc[ai][bj][m][n] = __builtin_amdgcn_mfma_f32_16x16x32_bf16(Bt[n][k], At[m][k], acc[ai][bj][m][n], 0, 0, 0); __builtin_amdgcn_s_setprio(0); } while (0)
; #define PG8_WAIT_V(n) asm volatile("s_waitcnt vmcnt(" #n ")" ::: "memory")
; #define PG8_WAIT_L(n) asm volatile("s_waitcnt lgkmcnt(" #n ")" ::: "memory")
; template <class Epi, class Sched, bool ALIGN_EPI = false, bool SP2 = false>
; __device__ __forceinline__ void gemm_phase(PG8_LAS unsigned char* lds, const Gemm g, const Sched& S, const Epi& E, const int tid_in) {
;     ...
;             const bool last = (t == nt - 2);
;             const char* a1 = cA + (size_t)(t + 1) * kstep;
;             const char* a2 = last ? nA : cA + (size_t)(t + 2) * kstep; const char* b2 = last ? nB : cB + (size_t)(t + 2) * kstep;
;             const char* a3 = a2 + kstep; const char* b3 = b2 + kstep;
;             if (last && has_next) S.a_ready(nxt);
;             if constexpr (SP2) {
;             PG8_LDB(B0, 0, 0); PG8_LDB(B1, 0, 1); PG8_SCHED; PG8_LDA(At, 0, 0); PG8_STAGE(PG8_SA(1, 1), a1 + hstep, voffA);
;             PG8_WAIT_V(8); PG8_WAIT_L(0); PG8_BAR; PG8_MMA(0, 0, At, B0); PG8_MMA(0, 1, At, B1); PG8_BAR; PG8_SCHED;
;             PG8_LDA(At, 0, 1); PG8_STAGE(PG8_SB(0, 0), b2, voffB); PG8_STAGE(PG8_SB(0, 1), b2 + hstep, voffB); PG8_STAGE(PG8_SA(0, 0), a2, voffA);
;             PG8_WAIT_V(8); PG8_WAIT_L(0); PG8_BAR; PG8_MMA(1, 0, At, B0); PG8_MMA(1, 1, At, B1); PG8_BAR; PG8_SCHED;
.LBB0_93:
	s_add_u32 s12, s42, 0xfffc0080
	s_addc_u32 s13, s43, -1
	s_add_i32 s46, 0, 0x10000
	s_cmp_eq_u32 s45, 12
	s_cselect_b32 s15, s11, s13
	s_cselect_b32 s14, s16, s12
	v_add_u32_e32 v148, s46, v150
	s_cselect_b32 s13, s17, s39
	s_cselect_b32 s12, s21, s25
	s_add_i32 s48, 0, 0x14000
	ds_read_b128 v[144:147], v148
	ds_read_b128 v[154:157], v148 offset:1024
	ds_read_b128 v[158:161], v148 offset:2048
	ds_read_b128 v[162:165], v148 offset:3072
	v_add_u32_e32 v148, s48, v150
	ds_read_b128 v[166:169], v148
	ds_read_b128 v[170:173], v148 offset:1024
	ds_read_b128 v[174:177], v148 offset:2048
	ds_read_b128 v[178:181], v148 offset:3072
	v_lshl_add_u64 v[148:149], s[42:43], 0, v[140:141]
	s_add_i32 m0, s22, 0xc000
	ds_read_b128 v[182:185], v152
	ds_read_b128 v[186:189], v152 offset:1024
	ds_read_b128 v[190:193], v152 offset:2048
	ds_read_b128 v[198:201], v152 offset:3072
	ds_read_b128 v[202:205], v152 offset:4096
	ds_read_b128 v[206:209], v152 offset:5120
	ds_read_b128 v[210:213], v152 offset:6144
	ds_read_b128 v[214:217], v152 offset:7168
	global_load_lds_dwordx4 v[148:149], off
	v_lshl_add_u64 v[148:149], s[42:43], 0, v[142:143]
	s_add_i32 m0, s22, 0xe000
	s_nop 0
	global_load_lds_dwordx4 v[148:149], off
	s_nop 0
	s_waitcnt vmcnt(8)
	s_waitcnt lgkmcnt(0)
	s_barrier
	v_mfma_f32_16x16x32_bf16 v[130:133], v[144:147], v[182:185], v[130:133]
	v_mfma_f32_16x16x32_bf16 v[130:133], v[154:157], v[186:189], v[130:133]
	v_mfma_f32_16x16x32_bf16 v[114:117], v[144:147], v[190:193], v[114:117]
	v_mfma_f32_16x16x32_bf16 v[114:117], v[154:157], v[198:201], v[114:117]
	v_mfma_f32_16x16x32_bf16 v[98:101], v[144:147], v[202:205], v[98:101]
	v_mfma_f32_16x16x32_bf16 v[98:101], v[154:157], v[206:209], v[98:101]
	v_mfma_f32_16x16x32_bf16 v[82:85], v[144:147], v[210:213], v[82:85]
	v_mfma_f32_16x16x32_bf16 v[82:85], v[154:157], v[214:217], v[82:85]
	v_mfma_f32_16x16x32_bf16 v[126:129], v[158:161], v[182:185], v[126:129]
	v_mfma_f32_16x16x32_bf16 v[126:129], v[162:165], v[186:189], v[126:129]
	v_mfma_f32_16x16x32_bf16 v[110:113], v[158:161], v[190:193], v[110:113]
	v_mfma_f32_16x16x32_bf16 v[110:113], v[162:165], v[198:201], v[110:113]
	v_mfma_f32_16x16x32_bf16 v[94:97], v[158:161], v[202:205], v[94:97]
	v_mfma_f32_16x16x32_bf16 v[94:97], v[162:165], v[206:209], v[94:97]
	v_mfma_f32_16x16x32_bf16 v[78:81], v[158:161], v[210:213], v[78:81]
	v_mfma_f32_16x16x32_bf16 v[78:81], v[162:165], v[214:217], v[78:81]
	v_mfma_f32_16x16x32_bf16 v[122:125], v[166:169], v[182:185], v[122:125]
	v_mfma_f32_16x16x32_bf16 v[122:125], v[170:173], v[186:189], v[122:125]
	v_mfma_f32_16x16x32_bf16 v[106:109], v[166:169], v[190:193], v[106:109]
	v_mfma_f32_16x16x32_bf16 v[106:109], v[170:173], v[198:201], v[106:109]
	v_mfma_f32_16x16x32_bf16 v[90:93], v[166:169], v[202:205], v[90:93]
	v_mfma_f32_16x16x32_bf16 v[90:93], v[170:173], v[206:209], v[90:93]
	v_mfma_f32_16x16x32_bf16 v[74:77], v[166:169], v[210:213], v[74:77]
	v_mfma_f32_16x16x32_bf16 v[74:77], v[170:173], v[214:217], v[74:77]
	v_mfma_f32_16x16x32_bf16 v[118:121], v[174:177], v[182:185], v[118:121]
	v_mfma_f32_16x16x32_bf16 v[118:121], v[178:181], v[186:189], v[118:121]
	v_mfma_f32_16x16x32_bf16 v[102:105], v[174:177], v[190:193], v[102:105]
	v_mfma_f32_16x16x32_bf16 v[102:105], v[178:181], v[198:201], v[102:105]
	v_mfma_f32_16x16x32_bf16 v[86:89], v[174:177], v[202:205], v[86:89]
	v_mfma_f32_16x16x32_bf16 v[86:89], v[178:181], v[206:209], v[86:89]
	v_mfma_f32_16x16x32_bf16 v[70:73], v[174:177], v[210:213], v[70:73]
	v_mfma_f32_16x16x32_bf16 v[70:73], v[178:181], v[214:217], v[70:73]
	s_barrier
	s_add_i32 s46, s46, s19
	v_lshl_add_u64 v[148:149], s[12:13], 0, v[134:135]
	s_mov_b32 m0, s46
	ds_read_b128 v[182:185], v152 offset:16384
	ds_read_b128 v[186:189], v152 offset:17408
	ds_read_b128 v[190:193], v152 offset:18432
	ds_read_b128 v[198:201], v152 offset:19456
	ds_read_b128 v[202:205], v152 offset:20480
	ds_read_b128 v[206:209], v152 offset:21504
	ds_read_b128 v[210:213], v152 offset:22528
	ds_read_b128 v[214:217], v152 offset:23552
	global_load_lds_dwordx4 v[148:149], off
	s_add_i32 m0, s46, 0x2000
	s_add_u32 s46, s12, 0x40000
	v_lshl_add_u64 v[218:219], s[12:13], 0, v[138:139]
	s_addc_u32 s47, s13, 0
	s_add_i32 s48, s48, s19
	global_load_lds_dwordx4 v[218:219], off
	v_lshl_add_u64 v[220:221], s[46:47], 0, v[134:135]
	s_mov_b32 m0, s48
	v_lshl_add_u64 v[222:223], s[14:15], 0, v[136:137]
	global_load_lds_dwordx4 v[220:221], off
	v_lshl_add_u64 v[220:221], s[46:47], 0, v[138:139]
	s_add_i32 m0, s48, 0x2000
	s_nop 0
	global_load_lds_dwordx4 v[220:221], off
	v_lshl_add_u64 v[220:221], s[14:15], 0, v[2:3]
	s_mov_b32 m0, s22
	s_nop 0
	global_load_lds_dwordx4 v[220:221], off
	s_mov_b32 m0, s23
	s_nop 0
	global_load_lds_dwordx4 v[222:223], off
	s_waitcnt vmcnt(8)
	s_waitcnt lgkmcnt(0)
	s_barrier
; #define PG8_STAGE(bufoff, gbase, voff) do { _Pragma("unroll") for (int _i = 0; _i < 2; ++_i) \
;         __builtin_amdgcn_global_load_lds((const unsigned*)((const char*)(gbase) + (voff)[_i]), (PG8_LAS unsigned*)(lds + (bufoff) + ldsw + _i * 8192), 16, 0, 0); } while (0)
; #define PG8_LDA(dst, b, h) do { _Pragma("unroll") for (int m = 0; m < 4; ++m) _Pragma("unroll") for (int k = 0; k < 2; ++k) dst[m][k] = *(const PG8_LAS bf16x8*)(lds + PG8_SA(b, h) + aoff + m * 2048 + k * 1024); } while (0)
; #define PG8_LDB(dst, b, h) do { _Pragma("unroll") for (int n = 0; n < 2; ++n) _Pragma("unroll") for (int k = 0; k < 2; ++k) dst[n][k] = *(const PG8_LAS bf16x8*)(lds + PG8_SB(b, h) + boff + n * 2048 + k * 1024); } while (0)
; #define PG8_MMA(ai, bj, At, Bt) do { __builtin_amdgcn_s_setprio(1); _Pragma("unroll") for (int m = 0; m < 4; ++m) _Pragma("unroll") for (int n = 0; n < 2; ++n) _Pragma("unroll") for (int k = 0; k < 2; ++k) \
;         acc[ai][bj][m][n] = __builtin_amdgcn_mfma_f32_16x16x32_bf16(Bt[n][k], At[m][k], acc[ai][bj][m][n], 0, 0, 0); __builtin_amdgcn_s_setprio(0); } while (0)
; #define PG8_WAIT_V(n) asm volatile("s_waitcnt vmcnt(" #n ")" ::: "memory")
; #define PG8_WAIT_L(n) asm volatile("s_waitcnt lgkmcnt(" #n ")" ::: "memory")
; #define PG8_BAR __builtin_amdgcn_s_barrier()
; #define PG8_SCHED __builtin_amdgcn_sched_barrier(0)
; template <class Epi, class Sched, bool ALIGN_EPI = false, bool SP2 = false>
; __device__ __forceinline__ void gemm_phase(PG8_LAS unsigned char* lds, const Gemm g, const Sched& S, const Epi& E, const int tid_in) {
;     ...
;             PG8_WAIT_V(8); PG8_WAIT_L(0); PG8_BAR; PG8_MMA(1, 0, At, B0); PG8_MMA(1, 1, At, B1); PG8_BAR; PG8_SCHED;
;             PG8_LDB(B0, 1, 0); PG8_LDB(B1, 1, 1); PG8_SCHED; PG8_LDA(At, 1, 0); PG8_STAGE(PG8_SA(0, 1), a2 + hstep, voffA);
	v_mfma_f32_16x16x32_bf16 v[66:69], v[144:147], v[182:185], v[66:69]
	v_mfma_f32_16x16x32_bf16 v[66:69], v[154:157], v[186:189], v[66:69]
	v_mfma_f32_16x16x32_bf16 v[50:53], v[144:147], v[190:193], v[50:53]
	v_mfma_f32_16x16x32_bf16 v[50:53], v[154:157], v[198:201], v[50:53]
	v_mfma_f32_16x16x32_bf16 v[34:37], v[144:147], v[202:205], v[34:37]
	v_mfma_f32_16x16x32_bf16 v[34:37], v[154:157], v[206:209], v[34:37]
	v_mfma_f32_16x16x32_bf16 v[18:21], v[144:147], v[210:213], v[18:21]
	v_mfma_f32_16x16x32_bf16 v[18:21], v[154:157], v[214:217], v[18:21]
	v_mfma_f32_16x16x32_bf16 v[62:65], v[158:161], v[182:185], v[62:65]
	v_mfma_f32_16x16x32_bf16 v[62:65], v[162:165], v[186:189], v[62:65]
	v_mfma_f32_16x16x32_bf16 v[46:49], v[158:161], v[190:193], v[46:49]
	v_mfma_f32_16x16x32_bf16 v[46:49], v[162:165], v[198:201], v[46:49]
	v_mfma_f32_16x16x32_bf16 v[30:33], v[158:161], v[202:205], v[30:33]
	v_mfma_f32_16x16x32_bf16 v[30:33], v[162:165], v[206:209], v[30:33]
	v_mfma_f32_16x16x32_bf16 v[14:17], v[158:161], v[210:213], v[14:17]
	v_mfma_f32_16x16x32_bf16 v[14:17], v[162:165], v[214:217], v[14:17]
	v_mfma_f32_16x16x32_bf16 v[58:61], v[166:169], v[182:185], v[58:61]
	v_mfma_f32_16x16x32_bf16 v[58:61], v[170:173], v[186:189], v[58:61]
	v_mfma_f32_16x16x32_bf16 v[42:45], v[166:169], v[190:193], v[42:45]
	v_mfma_f32_16x16x32_bf16 v[42:45], v[170:173], v[198:201], v[42:45]
	v_mfma_f32_16x16x32_bf16 v[26:29], v[166:169], v[202:205], v[26:29]
	v_mfma_f32_16x16x32_bf16 v[26:29], v[170:173], v[206:209], v[26:29]
	v_mfma_f32_16x16x32_bf16 v[10:13], v[166:169], v[210:213], v[10:13]
	v_mfma_f32_16x16x32_bf16 v[10:13], v[170:173], v[214:217], v[10:13]
	v_mfma_f32_16x16x32_bf16 v[54:57], v[174:177], v[182:185], v[54:57]
	v_mfma_f32_16x16x32_bf16 v[54:57], v[178:181], v[186:189], v[54:57]
	v_mfma_f32_16x16x32_bf16 v[38:41], v[174:177], v[190:193], v[38:41]
	v_mfma_f32_16x16x32_bf16 v[38:41], v[178:181], v[198:201], v[38:41]
	v_mfma_f32_16x16x32_bf16 v[22:25], v[174:177], v[202:205], v[22:25]
	v_mfma_f32_16x16x32_bf16 v[22:25], v[178:181], v[206:209], v[22:25]
	v_mfma_f32_16x16x32_bf16 v[6:9], v[174:177], v[210:213], v[6:9]
	v_mfma_f32_16x16x32_bf16 v[6:9], v[178:181], v[214:217], v[6:9]
	s_barrier
	s_add_i32 s46, 0, 0x18000
	v_add_u32_e32 v153, s46, v150
	s_add_i32 s47, 0, 0x1c000
	ds_read_b128 v[144:147], v153
	ds_read_b128 v[154:157], v153 offset:1024
	ds_read_b128 v[158:161], v153 offset:2048
	ds_read_b128 v[162:165], v153 offset:3072
	v_add_u32_e32 v153, s47, v150
	ds_read_b128 v[166:169], v153
	ds_read_b128 v[170:173], v153 offset:1024
	ds_read_b128 v[174:177], v153 offset:2048
	ds_read_b128 v[178:181], v153 offset:3072
	s_add_u32 s14, s14, 0x40000
	s_addc_u32 s15, s15, 0
	s_mov_b32 m0, s26
	v_lshl_add_u64 v[224:225], s[14:15], 0, v[2:3]
	ds_read_b128 v[182:185], v152 offset:32768
	ds_read_b128 v[186:189], v152 offset:33792
	ds_read_b128 v[190:193], v152 offset:34816
	ds_read_b128 v[198:201], v152 offset:35840
	ds_read_b128 v[202:205], v152 offset:36864
	ds_read_b128 v[206:209], v152 offset:37888
	ds_read_b128 v[210:213], v152 offset:38912
	ds_read_b128 v[214:217], v152 offset:39936
	global_load_lds_dwordx4 v[224:225], off
	v_lshl_add_u64 v[224:225], s[14:15], 0, v[136:137]
	s_mov_b32 m0, s27
	s_nop 0
	global_load_lds_dwordx4 v[224:225], off
	s_waitcnt vmcnt(8)
	s_waitcnt lgkmcnt(0)
	s_barrier
; #define PG8_STAGE(bufoff, gbase, voff) do { _Pragma("unroll") for (int _i = 0; _i < 2; ++_i) \
;         __builtin_amdgcn_global_load_lds((const unsigned*)((const char*)(gbase) + (voff)[_i]), (PG8_LAS unsigned*)(lds + (bufoff) + ldsw + _i * 8192), 16, 0, 0); } while (0)
; #define PG8_LDA(dst, b, h) do { _Pragma("unroll") for (int m = 0; m < 4; ++m) _Pragma("unroll") for (int k = 0; k < 2; ++k) dst[m][k] = *(const PG8_LAS bf16x8*)(lds + PG8_SA(b, h) + aoff + m * 2048 + k * 1024); } while (0)
; #define PG8_MMA(ai, bj, At, Bt) do { __builtin_amdgcn_s_setprio(1); _Pragma("unroll") for (int m = 0; m < 4; ++m) _Pragma("unroll") for (int n = 0; n < 2; ++n) _Pragma("unroll") for (int k = 0; k < 2; ++k) \
;         acc[ai][bj][m][n] = __builtin_amdgcn_mfma_f32_16x16x32_bf16(Bt[n][k], At[m][k], acc[ai][bj][m][n], 0, 0, 0); __builtin_amdgcn_s_setprio(0); } while (0)
; #define PG8_WAIT_V(n) asm volatile("s_waitcnt vmcnt(" #n ")" ::: "memory")
; #define PG8_WAIT_L(n) asm volatile("s_waitcnt lgkmcnt(" #n ")" ::: "memory")
; #define PG8_BAR __builtin_amdgcn_s_barrier()
; #define PG8_SCHED __builtin_amdgcn_sched_barrier(0)
; template <class Epi, class Sched, bool ALIGN_EPI = false, bool SP2 = false>
; __device__ __forceinline__ void gemm_phase(PG8_LAS unsigned char* lds, const Gemm g, const Sched& S, const Epi& E, const int tid_in) {
;     ...
;             PG8_WAIT_V(8); PG8_WAIT_L(0); PG8_BAR; PG8_MMA(0, 0, At, B0); PG8_MMA(0, 1, At, B1); PG8_BAR; PG8_SCHED;
;             PG8_LDA(At, 1, 1); PG8_STAGE(PG8_SB(1, 0), b3, voffB); PG8_STAGE(PG8_SB(1, 1), b3 + hstep, voffB); PG8_STAGE(PG8_SA(1, 0), a3, voffA);
;     __device__ __forceinline__ void operator()(const f32x4 (&acc)[2][2][4][2], const Unit& u, int wr, int wc, int fr, int fq) const {
;     ...
;         for (int ai = 0; ai < 2; ++ai)
; #pragma unroll
;             for (int m = 0; m < 4; ++m) rs[ai][m] = rowss[row0 + ai * HALF + m * 16];
	v_mfma_f32_16x16x32_bf16 v[130:133], v[144:147], v[182:185], v[130:133]
	v_mfma_f32_16x16x32_bf16 v[130:133], v[154:157], v[186:189], v[130:133]
	v_mfma_f32_16x16x32_bf16 v[114:117], v[144:147], v[190:193], v[114:117]
	v_mfma_f32_16x16x32_bf16 v[114:117], v[154:157], v[198:201], v[114:117]
	v_mfma_f32_16x16x32_bf16 v[98:101], v[144:147], v[202:205], v[98:101]
	v_mfma_f32_16x16x32_bf16 v[98:101], v[154:157], v[206:209], v[98:101]
	v_mfma_f32_16x16x32_bf16 v[82:85], v[144:147], v[210:213], v[82:85]
	v_mfma_f32_16x16x32_bf16 v[82:85], v[154:157], v[214:217], v[82:85]
	v_mfma_f32_16x16x32_bf16 v[126:129], v[158:161], v[182:185], v[126:129]
	v_mfma_f32_16x16x32_bf16 v[126:129], v[162:165], v[186:189], v[126:129]
	v_mfma_f32_16x16x32_bf16 v[110:113], v[158:161], v[190:193], v[110:113]
	v_mfma_f32_16x16x32_bf16 v[110:113], v[162:165], v[198:201], v[110:113]
	v_mfma_f32_16x16x32_bf16 v[94:97], v[158:161], v[202:205], v[94:97]
	v_mfma_f32_16x16x32_bf16 v[94:97], v[162:165], v[206:209], v[94:97]
	v_mfma_f32_16x16x32_bf16 v[78:81], v[158:161], v[210:213], v[78:81]
	v_mfma_f32_16x16x32_bf16 v[78:81], v[162:165], v[214:217], v[78:81]
	v_mfma_f32_16x16x32_bf16 v[122:125], v[166:169], v[182:185], v[122:125]
	v_mfma_f32_16x16x32_bf16 v[122:125], v[170:173], v[186:189], v[122:125]
	v_mfma_f32_16x16x32_bf16 v[106:109], v[166:169], v[190:193], v[106:109]
	v_mfma_f32_16x16x32_bf16 v[106:109], v[170:173], v[198:201], v[106:109]
	v_mfma_f32_16x16x32_bf16 v[90:93], v[166:169], v[202:205], v[90:93]
	v_mfma_f32_16x16x32_bf16 v[90:93], v[170:173], v[206:209], v[90:93]
	v_mfma_f32_16x16x32_bf16 v[74:77], v[166:169], v[210:213], v[74:77]
	v_mfma_f32_16x16x32_bf16 v[74:77], v[170:173], v[214:217], v[74:77]
	v_mfma_f32_16x16x32_bf16 v[118:121], v[174:177], v[182:185], v[118:121]
	v_mfma_f32_16x16x32_bf16 v[118:121], v[178:181], v[186:189], v[118:121]
	v_mfma_f32_16x16x32_bf16 v[102:105], v[174:177], v[190:193], v[102:105]
	v_mfma_f32_16x16x32_bf16 v[102:105], v[178:181], v[198:201], v[102:105]
	v_mfma_f32_16x16x32_bf16 v[86:89], v[174:177], v[202:205], v[86:89]
	v_mfma_f32_16x16x32_bf16 v[86:89], v[178:181], v[206:209], v[86:89]
	v_mfma_f32_16x16x32_bf16 v[70:73], v[174:177], v[210:213], v[70:73]
	v_mfma_f32_16x16x32_bf16 v[70:73], v[178:181], v[214:217], v[70:73]
	s_barrier
	s_add_i32 s14, s46, s19
	v_lshl_add_u64 v[148:149], v[148:149], 0, s[28:29]
	s_mov_b32 m0, s14
	ds_read_b128 v[182:185], v152 offset:49152
	ds_read_b128 v[186:189], v152 offset:50176
	ds_read_b128 v[190:193], v152 offset:51200
	ds_read_b128 v[198:201], v152 offset:52224
	ds_read_b128 v[202:205], v152 offset:53248
	ds_read_b128 v[206:209], v152 offset:54272
	ds_read_b128 v[210:213], v152 offset:55296
	ds_read_b128 v[214:217], v152 offset:56320
	global_load_lds_dwordx4 v[148:149], off
	s_add_i32 m0, s14, 0x2000
	s_add_u32 s12, s12, 0x40080
	v_lshl_add_u64 v[148:149], v[218:219], 0, s[28:29]
	s_addc_u32 s13, s13, 0
	s_add_i32 s14, s47, s19
	global_load_lds_dwordx4 v[148:149], off
	v_lshl_add_u64 v[148:149], s[12:13], 0, v[134:135]
	s_mov_b32 m0, s14
	s_nop 0
	global_load_lds_dwordx4 v[148:149], off
	v_lshl_add_u64 v[148:149], s[12:13], 0, v[138:139]
	s_add_i32 m0, s14, 0x2000
	s_nop 0
	global_load_lds_dwordx4 v[148:149], off
	v_lshl_add_u64 v[148:149], v[220:221], 0, s[28:29]
	s_mov_b32 m0, s30
	s_nop 0
	global_load_lds_dwordx4 v[148:149], off
	v_lshl_add_u64 v[148:149], v[222:223], 0, s[28:29]
	s_mov_b32 m0, s31
	s_nop 0
	global_load_lds_dwordx4 v[148:149], off
	s_waitcnt vmcnt(8)
	s_waitcnt lgkmcnt(0)
	s_cmp_lg_u32 s45, 12
	s_cbranch_scc1 .Lrs_in_skip
	v_lshl_add_u32 v148, s38, 8, v5
	v_ashrrev_i32_e32 v149, 31, v148
	v_lshl_add_u64 v[148:149], v[148:149], 2, s[6:7]
	global_load_dword v226, v[148:149], off
	global_load_dword v227, v[148:149], off offset:64
	global_load_dword v228, v[148:149], off offset:128
	global_load_dword v229, v[148:149], off offset:192
	global_load_dword v238, v[148:149], off offset:512
	global_load_dword v239, v[148:149], off offset:576
	global_load_dword v240, v[148:149], off offset:640
	global_load_dword v241, v[148:149], off offset:704

; #define PG8_STAGE(bufoff, gbase, voff) do { _Pragma("unroll") for (int _i = 0; _i < 2; ++_i) \
;         __builtin_amdgcn_global_load_lds((const unsigned*)((const char*)(gbase) + (voff)[_i]), (PG8_LAS unsigned*)(lds + (bufoff) + ldsw + _i * 8192), 16, 0, 0); } while (0)
; #define PG8_LDA(dst, b, h) do { _Pragma("unroll") for (int m = 0; m < 4; ++m) _Pragma("unroll") for (int k = 0; k < 2; ++k) dst[m][k] = *(const PG8_LAS bf16x8*)(lds + PG8_SA(b, h) + aoff + m * 2048 + k * 1024); } while (0)
; #define PG8_LDB(dst, b, h) do { _Pragma("unroll") for (int n = 0; n < 2; ++n) _Pragma("unroll") for (int k = 0; k < 2; ++k) dst[n][k] = *(const PG8_LAS bf16x8*)(lds + PG8_SB(b, h) + boff + n * 2048 + k * 1024); } while (0)
; #define PG8_WAIT_V(n) asm volatile("s_waitcnt vmcnt(" #n ")" ::: "memory")
; #define PG8_WAIT_L(n) asm volatile("s_waitcnt lgkmcnt(" #n ")" ::: "memory")
; #define PG8_BAR __builtin_amdgcn_s_barrier()
; #define PG8_SCHED __builtin_amdgcn_sched_barrier(0)
; template <class Epi, class Sched, bool ALIGN_EPI = false, bool SP2 = false>
; __device__ __forceinline__ void gemm_phase(PG8_LAS unsigned char* lds, const Gemm g, const Sched& S, const Epi& E, const int tid_in) {
;     ...
;         const bool has_next = S.next(ui + 1, nxt);
;         const char* nA = has_next ? (const char*)g.A + (size_t)nxt.pm * tstep : cA; const char* nB = has_next ? (const char*)g.Bt + (size_t)nxt.pn * tstep : cB;
;         for (int t = 0; t < nt; t += 2) {
;             const bool last = (t == nt - 2);
;             const char* a1 = cA + (size_t)(t + 1) * kstep;
;             const char* a2 = last ? nA : cA + (size_t)(t + 2) * kstep; const char* b2 = last ? nB : cB + (size_t)(t + 2) * kstep;
;             const char* a3 = a2 + kstep; const char* b3 = b2 + kstep;
;             if (last && has_next) S.a_ready(nxt);
;             if constexpr (SP2) {
;             PG8_LDB(B0, 0, 0); PG8_LDB(B1, 0, 1); PG8_SCHED; PG8_LDA(At, 0, 0); PG8_STAGE(PG8_SA(1, 1), a1 + hstep, voffA);
;             PG8_WAIT_V(8); PG8_WAIT_L(0); PG8_BAR; PG8_MMA(0, 0, At, B0); PG8_MMA(0, 1, At, B1); PG8_BAR; PG8_SCHED;
;             PG8_LDA(At, 0, 1); PG8_STAGE(PG8_SB(0, 0), b2, voffB); PG8_STAGE(PG8_SB(0, 1), b2 + hstep, voffB); PG8_STAGE(PG8_SA(0, 0), a2, voffA);
;             PG8_WAIT_V(8); PG8_WAIT_L(0); PG8_BAR; PG8_MMA(1, 0, At, B0); PG8_MMA(1, 1, At, B1); PG8_BAR; PG8_SCHED;
.LBB0_153:
	s_ashr_i32 s25, s24, 31
	s_lshl_b64 s[14:15], s[24:25], 19
	s_add_u32 s34, s84, s14
	s_addc_u32 s35, s85, s15
	s_and_b64 s[14:15], s[36:37], exec
	s_cselect_b32 s25, s35, s11
	s_cselect_b32 s41, s34, s10
	s_ashr_i32 s21, s20, 31
	s_lshl_b64 s[14:15], s[20:21], 19
	s_add_u32 s38, s3, s14
	s_addc_u32 s39, s16, s15
	s_and_b64 s[14:15], s[36:37], exec
	s_cselect_b32 s21, s39, s13
	s_cselect_b32 s42, s38, s12
	s_add_u32 s10, s10, 0x40080
	s_addc_u32 s11, s11, 0
	s_add_u32 s43, s12, 0x100
	s_addc_u32 s44, s13, 0
	s_mov_b32 s45, -2
	s_add_u32 s12, s10, 0xfffc0080
	s_addc_u32 s13, s11, -1
	s_add_i32 s46, 0, 0x10000
	s_cmp_eq_u32 s45, 12
	s_cselect_b32 s15, s25, s13
	s_cselect_b32 s14, s41, s12
	v_add_u32_e32 v144, s46, v146
	s_cselect_b32 s13, s21, s44
	s_cselect_b32 s12, s42, s43
	s_add_i32 s48, 0, 0x14000
	ds_read_b128 v[150:153], v144
	ds_read_b128 v[154:157], v144 offset:1024
	ds_read_b128 v[158:161], v144 offset:2048
	ds_read_b128 v[162:165], v144 offset:3072
	v_add_u32_e32 v144, s48, v146
	ds_read_b128 v[166:169], v144
	ds_read_b128 v[170:173], v144 offset:1024
	ds_read_b128 v[174:177], v144 offset:2048
	ds_read_b128 v[178:181], v144 offset:3072
	v_lshl_add_u64 v[144:145], s[10:11], 0, v[140:141]
	s_add_i32 m0, s18, 0xc000
	ds_read_b128 v[182:185], v148
	ds_read_b128 v[186:189], v148 offset:1024
	ds_read_b128 v[190:193], v148 offset:2048
	ds_read_b128 v[198:201], v148 offset:3072
	ds_read_b128 v[202:205], v148 offset:4096
	ds_read_b128 v[206:209], v148 offset:5120
	ds_read_b128 v[210:213], v148 offset:6144
	ds_read_b128 v[214:217], v148 offset:7168
	global_load_lds_dwordx4 v[144:145], off
	v_lshl_add_u64 v[144:145], s[10:11], 0, v[142:143]
	s_add_i32 m0, s18, 0xe000
	s_nop 0
	global_load_lds_dwordx4 v[144:145], off
	s_nop 0
	s_waitcnt vmcnt(8)
	s_waitcnt lgkmcnt(0)
	s_barrier
	v_mfma_f32_16x16x32_bf16 v[130:133], v[150:153], v[182:185], 0
	v_mfma_f32_16x16x32_bf16 v[130:133], v[154:157], v[186:189], v[130:133]
	v_mfma_f32_16x16x32_bf16 v[114:117], v[150:153], v[190:193], 0
	v_mfma_f32_16x16x32_bf16 v[114:117], v[154:157], v[198:201], v[114:117]
	v_mfma_f32_16x16x32_bf16 v[98:101], v[150:153], v[202:205], 0
	v_mfma_f32_16x16x32_bf16 v[98:101], v[154:157], v[206:209], v[98:101]
	v_mfma_f32_16x16x32_bf16 v[82:85], v[150:153], v[210:213], 0
	v_mfma_f32_16x16x32_bf16 v[82:85], v[154:157], v[214:217], v[82:85]
	v_mfma_f32_16x16x32_bf16 v[126:129], v[158:161], v[182:185], 0
	v_mfma_f32_16x16x32_bf16 v[126:129], v[162:165], v[186:189], v[126:129]
	v_mfma_f32_16x16x32_bf16 v[106:109], v[158:161], v[190:193], 0
	v_mfma_f32_16x16x32_bf16 v[106:109], v[162:165], v[198:201], v[106:109]
	v_mfma_f32_16x16x32_bf16 v[94:97], v[158:161], v[202:205], 0
	v_mfma_f32_16x16x32_bf16 v[94:97], v[162:165], v[206:209], v[94:97]
	v_mfma_f32_16x16x32_bf16 v[78:81], v[158:161], v[210:213], 0
	v_mfma_f32_16x16x32_bf16 v[78:81], v[162:165], v[214:217], v[78:81]
	v_mfma_f32_16x16x32_bf16 v[122:125], v[166:169], v[182:185], 0
	v_mfma_f32_16x16x32_bf16 v[122:125], v[170:173], v[186:189], v[122:125]
	v_mfma_f32_16x16x32_bf16 v[110:113], v[166:169], v[190:193], 0
	v_mfma_f32_16x16x32_bf16 v[110:113], v[170:173], v[198:201], v[110:113]
	v_mfma_f32_16x16x32_bf16 v[90:93], v[166:169], v[202:205], 0
	v_mfma_f32_16x16x32_bf16 v[90:93], v[170:173], v[206:209], v[90:93]
	v_mfma_f32_16x16x32_bf16 v[74:77], v[166:169], v[210:213], 0
	v_mfma_f32_16x16x32_bf16 v[74:77], v[170:173], v[214:217], v[74:77]
	v_mfma_f32_16x16x32_bf16 v[118:121], v[174:177], v[182:185], 0
	v_mfma_f32_16x16x32_bf16 v[118:121], v[178:181], v[186:189], v[118:121]
	v_mfma_f32_16x16x32_bf16 v[102:105], v[174:177], v[190:193], 0
	v_mfma_f32_16x16x32_bf16 v[102:105], v[178:181], v[198:201], v[102:105]
	v_mfma_f32_16x16x32_bf16 v[86:89], v[174:177], v[202:205], 0
	v_mfma_f32_16x16x32_bf16 v[86:89], v[178:181], v[206:209], v[86:89]
	v_mfma_f32_16x16x32_bf16 v[70:73], v[174:177], v[210:213], 0
	v_mfma_f32_16x16x32_bf16 v[70:73], v[178:181], v[214:217], v[70:73]
	s_barrier
	s_add_i32 s46, s46, s17
	v_lshl_add_u64 v[144:145], s[12:13], 0, v[136:137]
	s_mov_b32 m0, s46
	ds_read_b128 v[182:185], v148 offset:16384
	ds_read_b128 v[186:189], v148 offset:17408
	ds_read_b128 v[190:193], v148 offset:18432
	ds_read_b128 v[198:201], v148 offset:19456
	ds_read_b128 v[202:205], v148 offset:20480
	ds_read_b128 v[206:209], v148 offset:21504
	ds_read_b128 v[210:213], v148 offset:22528
	ds_read_b128 v[214:217], v148 offset:23552
	global_load_lds_dwordx4 v[144:145], off
	s_add_i32 m0, s46, 0x2000
	s_add_u32 s46, s12, 0x40000
	v_lshl_add_u64 v[218:219], s[12:13], 0, v[2:3]
	s_addc_u32 s47, s13, 0
	s_add_i32 s48, s48, s17
	global_load_lds_dwordx4 v[218:219], off
	v_lshl_add_u64 v[220:221], s[46:47], 0, v[136:137]
	s_mov_b32 m0, s48
	v_lshl_add_u64 v[222:223], s[14:15], 0, v[134:135]
	global_load_lds_dwordx4 v[220:221], off
	v_lshl_add_u64 v[220:221], s[46:47], 0, v[2:3]
	s_add_i32 m0, s48, 0x2000
	s_nop 0
	global_load_lds_dwordx4 v[220:221], off
	v_lshl_add_u64 v[220:221], s[14:15], 0, v[138:139]
	s_mov_b32 m0, s18
	s_nop 0
	global_load_lds_dwordx4 v[220:221], off
	s_mov_b32 m0, s19
	s_nop 0
	global_load_lds_dwordx4 v[222:223], off
	s_waitcnt vmcnt(8)
	s_waitcnt lgkmcnt(0)
	s_barrier
; #define PG8_STAGE(bufoff, gbase, voff) do { _Pragma("unroll") for (int _i = 0; _i < 2; ++_i) \
;         __builtin_amdgcn_global_load_lds((const unsigned*)((const char*)(gbase) + (voff)[_i]), (PG8_LAS unsigned*)(lds + (bufoff) + ldsw + _i * 8192), 16, 0, 0); } while (0)
; #define PG8_LDA(dst, b, h) do { _Pragma("unroll") for (int m = 0; m < 4; ++m) _Pragma("unroll") for (int k = 0; k < 2; ++k) dst[m][k] = *(const PG8_LAS bf16x8*)(lds + PG8_SA(b, h) + aoff + m * 2048 + k * 1024); } while (0)
; #define PG8_LDB(dst, b, h) do { _Pragma("unroll") for (int n = 0; n < 2; ++n) _Pragma("unroll") for (int k = 0; k < 2; ++k) dst[n][k] = *(const PG8_LAS bf16x8*)(lds + PG8_SB(b, h) + boff + n * 2048 + k * 1024); } while (0)
; #define PG8_MMA(ai, bj, At, Bt) do { __builtin_amdgcn_s_setprio(1); _Pragma("unroll") for (int m = 0; m < 4; ++m) _Pragma("unroll") for (int n = 0; n < 2; ++n) _Pragma("unroll") for (int k = 0; k < 2; ++k) \
;         acc[ai][bj][m][n] = __builtin_amdgcn_mfma_f32_16x16x32_bf16(Bt[n][k], At[m][k], acc[ai][bj][m][n], 0, 0, 0); __builtin_amdgcn_s_setprio(0); } while (0)
; #define PG8_WAIT_V(n) asm volatile("s_waitcnt vmcnt(" #n ")" ::: "memory")
; #define PG8_WAIT_L(n) asm volatile("s_waitcnt lgkmcnt(" #n ")" ::: "memory")
; #define PG8_BAR __builtin_amdgcn_s_barrier()
; #define PG8_SCHED __builtin_amdgcn_sched_barrier(0)
; template <class Epi, class Sched, bool ALIGN_EPI = false, bool SP2 = false>
; __device__ __forceinline__ void gemm_phase(PG8_LAS unsigned char* lds, const Gemm g, const Sched& S, const Epi& E, const int tid_in) {
;     ...
;             PG8_WAIT_V(8); PG8_WAIT_L(0); PG8_BAR; PG8_MMA(1, 0, At, B0); PG8_MMA(1, 1, At, B1); PG8_BAR; PG8_SCHED;
;             PG8_LDB(B0, 1, 0); PG8_LDB(B1, 1, 1); PG8_SCHED; PG8_LDA(At, 1, 0); PG8_STAGE(PG8_SA(0, 1), a2 + hstep, voffA);
;             PG8_WAIT_V(8); PG8_WAIT_L(0); PG8_BAR; PG8_MMA(0, 0, At, B0); PG8_MMA(0, 1, At, B1); PG8_BAR; PG8_SCHED;
	v_mfma_f32_16x16x32_bf16 v[66:69], v[150:153], v[182:185], 0
	v_mfma_f32_16x16x32_bf16 v[66:69], v[154:157], v[186:189], v[66:69]
	v_mfma_f32_16x16x32_bf16 v[50:53], v[150:153], v[190:193], 0
	v_mfma_f32_16x16x32_bf16 v[50:53], v[154:157], v[198:201], v[50:53]
	v_mfma_f32_16x16x32_bf16 v[34:37], v[150:153], v[202:205], 0
	v_mfma_f32_16x16x32_bf16 v[34:37], v[154:157], v[206:209], v[34:37]
	v_mfma_f32_16x16x32_bf16 v[18:21], v[150:153], v[210:213], 0
	v_mfma_f32_16x16x32_bf16 v[18:21], v[154:157], v[214:217], v[18:21]
	v_mfma_f32_16x16x32_bf16 v[62:65], v[158:161], v[182:185], 0
	v_mfma_f32_16x16x32_bf16 v[62:65], v[162:165], v[186:189], v[62:65]
	v_mfma_f32_16x16x32_bf16 v[46:49], v[158:161], v[190:193], 0
	v_mfma_f32_16x16x32_bf16 v[46:49], v[162:165], v[198:201], v[46:49]
	v_mfma_f32_16x16x32_bf16 v[30:33], v[158:161], v[202:205], 0
	v_mfma_f32_16x16x32_bf16 v[30:33], v[162:165], v[206:209], v[30:33]
	v_mfma_f32_16x16x32_bf16 v[14:17], v[158:161], v[210:213], 0
	v_mfma_f32_16x16x32_bf16 v[14:17], v[162:165], v[214:217], v[14:17]
	v_mfma_f32_16x16x32_bf16 v[58:61], v[166:169], v[182:185], 0
	v_mfma_f32_16x16x32_bf16 v[58:61], v[170:173], v[186:189], v[58:61]
	v_mfma_f32_16x16x32_bf16 v[42:45], v[166:169], v[190:193], 0
	v_mfma_f32_16x16x32_bf16 v[42:45], v[170:173], v[198:201], v[42:45]
	v_mfma_f32_16x16x32_bf16 v[26:29], v[166:169], v[202:205], 0
	v_mfma_f32_16x16x32_bf16 v[26:29], v[170:173], v[206:209], v[26:29]
	v_mfma_f32_16x16x32_bf16 v[10:13], v[166:169], v[210:213], 0
	v_mfma_f32_16x16x32_bf16 v[10:13], v[170:173], v[214:217], v[10:13]
	v_mfma_f32_16x16x32_bf16 v[54:57], v[174:177], v[182:185], 0
	v_mfma_f32_16x16x32_bf16 v[54:57], v[178:181], v[186:189], v[54:57]
	v_mfma_f32_16x16x32_bf16 v[38:41], v[174:177], v[190:193], 0
	v_mfma_f32_16x16x32_bf16 v[38:41], v[178:181], v[198:201], v[38:41]
	v_mfma_f32_16x16x32_bf16 v[22:25], v[174:177], v[202:205], 0
	v_mfma_f32_16x16x32_bf16 v[22:25], v[178:181], v[206:209], v[22:25]
	v_mfma_f32_16x16x32_bf16 v[6:9], v[174:177], v[210:213], 0
	v_mfma_f32_16x16x32_bf16 v[6:9], v[178:181], v[214:217], v[6:9]
	s_barrier
	s_add_i32 s46, 0, 0x18000
	v_add_u32_e32 v149, s46, v146
	s_add_i32 s47, 0, 0x1c000
	ds_read_b128 v[150:153], v149
	ds_read_b128 v[154:157], v149 offset:1024
	ds_read_b128 v[158:161], v149 offset:2048
	ds_read_b128 v[162:165], v149 offset:3072
	v_add_u32_e32 v149, s47, v146
	ds_read_b128 v[166:169], v149
	ds_read_b128 v[170:173], v149 offset:1024
	ds_read_b128 v[174:177], v149 offset:2048
	ds_read_b128 v[178:181], v149 offset:3072
	s_add_u32 s14, s14, 0x40000
	s_addc_u32 s15, s15, 0
	s_mov_b32 m0, s22
	v_lshl_add_u64 v[224:225], s[14:15], 0, v[138:139]
	ds_read_b128 v[182:185], v148 offset:32768
	ds_read_b128 v[186:189], v148 offset:33792
	ds_read_b128 v[190:193], v148 offset:34816
	ds_read_b128 v[198:201], v148 offset:35840
	ds_read_b128 v[202:205], v148 offset:36864
	ds_read_b128 v[206:209], v148 offset:37888
	ds_read_b128 v[210:213], v148 offset:38912
	ds_read_b128 v[214:217], v148 offset:39936
	global_load_lds_dwordx4 v[224:225], off
	v_lshl_add_u64 v[224:225], s[14:15], 0, v[134:135]
	s_mov_b32 m0, s23
	s_nop 0
	global_load_lds_dwordx4 v[224:225], off
	s_waitcnt vmcnt(8)
	s_waitcnt lgkmcnt(0)
	s_barrier
; #define PG8_STAGE(bufoff, gbase, voff) do { _Pragma("unroll") for (int _i = 0; _i < 2; ++_i) \
;         __builtin_amdgcn_global_load_lds((const unsigned*)((const char*)(gbase) + (voff)[_i]), (PG8_LAS unsigned*)(lds + (bufoff) + ldsw + _i * 8192), 16, 0, 0); } while (0)
; #define PG8_LDA(dst, b, h) do { _Pragma("unroll") for (int m = 0; m < 4; ++m) _Pragma("unroll") for (int k = 0; k < 2; ++k) dst[m][k] = *(const PG8_LAS bf16x8*)(lds + PG8_SA(b, h) + aoff + m * 2048 + k * 1024); } while (0)
; #define PG8_MMA(ai, bj, At, Bt) do { __builtin_amdgcn_s_setprio(1); _Pragma("unroll") for (int m = 0; m < 4; ++m) _Pragma("unroll") for (int n = 0; n < 2; ++n) _Pragma("unroll") for (int k = 0; k < 2; ++k) \
;         acc[ai][bj][m][n] = __builtin_amdgcn_mfma_f32_16x16x32_bf16(Bt[n][k], At[m][k], acc[ai][bj][m][n], 0, 0, 0); __builtin_amdgcn_s_setprio(0); } while (0)
; #define PG8_WAIT_V(n) asm volatile("s_waitcnt vmcnt(" #n ")" ::: "memory")
; #define PG8_WAIT_L(n) asm volatile("s_waitcnt lgkmcnt(" #n ")" ::: "memory")
; #define PG8_BAR __builtin_amdgcn_s_barrier()
; #define PG8_SCHED __builtin_amdgcn_sched_barrier(0)
; template <class Epi, class Sched, bool ALIGN_EPI = false, bool SP2 = false>
; __device__ __forceinline__ void gemm_phase(PG8_LAS unsigned char* lds, const Gemm g, const Sched& S, const Epi& E, const int tid_in) {
;     ...
;             PG8_WAIT_V(8); PG8_WAIT_L(0); PG8_BAR; PG8_MMA(0, 0, At, B0); PG8_MMA(0, 1, At, B1); PG8_BAR; PG8_SCHED;
;             PG8_LDA(At, 1, 1); PG8_STAGE(PG8_SB(1, 0), b3, voffB); PG8_STAGE(PG8_SB(1, 1), b3 + hstep, voffB); PG8_STAGE(PG8_SA(1, 0), a3, voffA);
;     __device__ __forceinline__ void operator()(const f32x4 (&acc)[2][2][4][2], const Unit& u, int wr, int wc, int fr, int fq) const {
;     ...
; #pragma unroll
;         for (int ai = 0; ai < 2; ++ai)
; #pragma unroll
;             for (int m = 0; m < 4; ++m) rs[ai][m] = rowss[row0 + ai * HALF + m * 16];
	v_mfma_f32_16x16x32_bf16 v[130:133], v[150:153], v[182:185], v[130:133]
	v_mfma_f32_16x16x32_bf16 v[130:133], v[154:157], v[186:189], v[130:133]
	v_mfma_f32_16x16x32_bf16 v[114:117], v[150:153], v[190:193], v[114:117]
	v_mfma_f32_16x16x32_bf16 v[114:117], v[154:157], v[198:201], v[114:117]
	v_mfma_f32_16x16x32_bf16 v[98:101], v[150:153], v[202:205], v[98:101]
	v_mfma_f32_16x16x32_bf16 v[98:101], v[154:157], v[206:209], v[98:101]
	v_mfma_f32_16x16x32_bf16 v[82:85], v[150:153], v[210:213], v[82:85]
	v_mfma_f32_16x16x32_bf16 v[82:85], v[154:157], v[214:217], v[82:85]
	v_mfma_f32_16x16x32_bf16 v[126:129], v[158:161], v[182:185], v[126:129]
	v_mfma_f32_16x16x32_bf16 v[126:129], v[162:165], v[186:189], v[126:129]
	v_mfma_f32_16x16x32_bf16 v[106:109], v[158:161], v[190:193], v[106:109]
	v_mfma_f32_16x16x32_bf16 v[106:109], v[162:165], v[198:201], v[106:109]
	v_mfma_f32_16x16x32_bf16 v[94:97], v[158:161], v[202:205], v[94:97]
	v_mfma_f32_16x16x32_bf16 v[94:97], v[162:165], v[206:209], v[94:97]
	v_mfma_f32_16x16x32_bf16 v[78:81], v[158:161], v[210:213], v[78:81]
	v_mfma_f32_16x16x32_bf16 v[78:81], v[162:165], v[214:217], v[78:81]
	v_mfma_f32_16x16x32_bf16 v[122:125], v[166:169], v[182:185], v[122:125]
	v_mfma_f32_16x16x32_bf16 v[122:125], v[170:173], v[186:189], v[122:125]
	v_mfma_f32_16x16x32_bf16 v[110:113], v[166:169], v[190:193], v[110:113]
	v_mfma_f32_16x16x32_bf16 v[110:113], v[170:173], v[198:201], v[110:113]
	v_mfma_f32_16x16x32_bf16 v[90:93], v[166:169], v[202:205], v[90:93]
	v_mfma_f32_16x16x32_bf16 v[90:93], v[170:173], v[206:209], v[90:93]
	v_mfma_f32_16x16x32_bf16 v[74:77], v[166:169], v[210:213], v[74:77]
	v_mfma_f32_16x16x32_bf16 v[74:77], v[170:173], v[214:217], v[74:77]
	v_mfma_f32_16x16x32_bf16 v[118:121], v[174:177], v[182:185], v[118:121]
	v_mfma_f32_16x16x32_bf16 v[118:121], v[178:181], v[186:189], v[118:121]
	v_mfma_f32_16x16x32_bf16 v[102:105], v[174:177], v[190:193], v[102:105]
	v_mfma_f32_16x16x32_bf16 v[102:105], v[178:181], v[198:201], v[102:105]
	v_mfma_f32_16x16x32_bf16 v[86:89], v[174:177], v[202:205], v[86:89]
	v_mfma_f32_16x16x32_bf16 v[86:89], v[178:181], v[206:209], v[86:89]
	v_mfma_f32_16x16x32_bf16 v[70:73], v[174:177], v[210:213], v[70:73]
	v_mfma_f32_16x16x32_bf16 v[70:73], v[178:181], v[214:217], v[70:73]
	s_barrier
	s_add_i32 s14, s46, s17
	v_lshl_add_u64 v[144:145], v[144:145], 0, s[28:29]
	s_mov_b32 m0, s14
	ds_read_b128 v[182:185], v148 offset:49152
	ds_read_b128 v[186:189], v148 offset:50176
	ds_read_b128 v[190:193], v148 offset:51200
	ds_read_b128 v[198:201], v148 offset:52224
	ds_read_b128 v[202:205], v148 offset:53248
	ds_read_b128 v[206:209], v148 offset:54272
	ds_read_b128 v[210:213], v148 offset:55296
	ds_read_b128 v[214:217], v148 offset:56320
	global_load_lds_dwordx4 v[144:145], off
	s_add_i32 m0, s14, 0x2000
	s_add_u32 s12, s12, 0x40080
	v_lshl_add_u64 v[144:145], v[218:219], 0, s[28:29]
	s_addc_u32 s13, s13, 0
	s_add_i32 s14, s47, s17
	global_load_lds_dwordx4 v[144:145], off
	v_lshl_add_u64 v[144:145], s[12:13], 0, v[136:137]
	s_mov_b32 m0, s14
	s_nop 0
	global_load_lds_dwordx4 v[144:145], off
	v_lshl_add_u64 v[144:145], s[12:13], 0, v[2:3]
	s_add_i32 m0, s14, 0x2000
	s_nop 0
	global_load_lds_dwordx4 v[144:145], off
	v_lshl_add_u64 v[144:145], v[220:221], 0, s[28:29]
	s_mov_b32 m0, s26
	s_nop 0
	global_load_lds_dwordx4 v[144:145], off
	v_lshl_add_u64 v[144:145], v[222:223], 0, s[28:29]
	s_mov_b32 m0, s27
	s_nop 0
	global_load_lds_dwordx4 v[144:145], off
	s_waitcnt vmcnt(8)
	s_waitcnt lgkmcnt(0)
	s_cmp_lg_u32 s45, 12
	s_cbranch_scc1 .Lrs_gu_skip_pgu
	v_lshl_add_u32 v144, s40, 8, v5
	v_ashrrev_i32_e32 v145, 31, v144
	v_lshl_add_u64 v[144:145], v[144:145], 2, s[6:7]
	global_load_dword v226, v[144:145], off
	global_load_dword v227, v[144:145], off offset:64
	global_load_dword v228, v[144:145], off offset:128
	global_load_dword v229, v[144:145], off offset:192
	global_load_dword v238, v[144:145], off offset:512
	global_load_dword v239, v[144:145], off offset:576
	global_load_dword v240, v[144:145], off offset:640
	global_load_dword v241, v[144:145], off offset:704

; #define PG8_STAGE(bufoff, gbase, voff) do { _Pragma("unroll") for (int _i = 0; _i < 2; ++_i) \
;         __builtin_amdgcn_global_load_lds((const unsigned*)((const char*)(gbase) + (voff)[_i]), (PG8_LAS unsigned*)(lds + (bufoff) + ldsw + _i * 8192), 16, 0, 0); } while (0)
; #define PG8_LDA(dst, b, h) do { _Pragma("unroll") for (int m = 0; m < 4; ++m) _Pragma("unroll") for (int k = 0; k < 2; ++k) dst[m][k] = *(const PG8_LAS bf16x8*)(lds + PG8_SA(b, h) + aoff + m * 2048 + k * 1024); } while (0)
; #define PG8_LDB(dst, b, h) do { _Pragma("unroll") for (int n = 0; n < 2; ++n) _Pragma("unroll") for (int k = 0; k < 2; ++k) dst[n][k] = *(const PG8_LAS bf16x8*)(lds + PG8_SB(b, h) + boff + n * 2048 + k * 1024); } while (0)
; #define PG8_MMA(ai, bj, At, Bt) do { __builtin_amdgcn_s_setprio(1); _Pragma("unroll") for (int m = 0; m < 4; ++m) _Pragma("unroll") for (int n = 0; n < 2; ++n) _Pragma("unroll") for (int k = 0; k < 2; ++k) \
;         acc[ai][bj][m][n] = __builtin_amdgcn_mfma_f32_16x16x32_bf16(Bt[n][k], At[m][k], acc[ai][bj][m][n], 0, 0, 0); __builtin_amdgcn_s_setprio(0); } while (0)
; #define PG8_WAIT_V(n) asm volatile("s_waitcnt vmcnt(" #n ")" ::: "memory")
; #define PG8_WAIT_L(n) asm volatile("s_waitcnt lgkmcnt(" #n ")" ::: "memory")
; template <class Epi, class Sched, bool ALIGN_EPI = false, bool SP2 = false>
; __device__ __forceinline__ void gemm_phase(PG8_LAS unsigned char* lds, const Gemm g, const Sched& S, const Epi& E, const int tid_in) {
;     ...
;             const bool last = (t == nt - 2);
;             const char* a1 = cA + (size_t)(t + 1) * kstep;
;             const char* a2 = last ? nA : cA + (size_t)(t + 2) * kstep; const char* b2 = last ? nB : cB + (size_t)(t + 2) * kstep;
;             const char* a3 = a2 + kstep; const char* b3 = b2 + kstep;
;             if (last && has_next) S.a_ready(nxt);
;             if constexpr (SP2) {
;             PG8_LDB(B0, 0, 0); PG8_LDB(B1, 0, 1); PG8_SCHED; PG8_LDA(At, 0, 0); PG8_STAGE(PG8_SA(1, 1), a1 + hstep, voffA);
;             PG8_WAIT_V(8); PG8_WAIT_L(0); PG8_BAR; PG8_MMA(0, 0, At, B0); PG8_MMA(0, 1, At, B1); PG8_BAR; PG8_SCHED;
;             PG8_LDA(At, 0, 1); PG8_STAGE(PG8_SB(0, 0), b2, voffB); PG8_STAGE(PG8_SB(0, 1), b2 + hstep, voffB); PG8_STAGE(PG8_SA(0, 0), a2, voffA);
;             PG8_WAIT_V(8); PG8_WAIT_L(0); PG8_BAR; PG8_MMA(1, 0, At, B0); PG8_MMA(1, 1, At, B1); PG8_BAR; PG8_SCHED;
.LBB0_154:
	s_add_u32 s12, s10, 0xfffc0080
	s_addc_u32 s13, s11, -1
	s_add_i32 s46, 0, 0x10000
	s_cmp_eq_u32 s45, 12
	s_cselect_b32 s15, s25, s13
	s_cselect_b32 s14, s41, s12
	v_add_u32_e32 v144, s46, v146
	s_cselect_b32 s13, s21, s44
	s_cselect_b32 s12, s42, s43
	s_add_i32 s48, 0, 0x14000
	ds_read_b128 v[150:153], v144
	ds_read_b128 v[154:157], v144 offset:1024
	ds_read_b128 v[158:161], v144 offset:2048
	ds_read_b128 v[162:165], v144 offset:3072
	v_add_u32_e32 v144, s48, v146
	ds_read_b128 v[166:169], v144
	ds_read_b128 v[170:173], v144 offset:1024
	ds_read_b128 v[174:177], v144 offset:2048
	ds_read_b128 v[178:181], v144 offset:3072
	v_lshl_add_u64 v[144:145], s[10:11], 0, v[140:141]
	s_add_i32 m0, s18, 0xc000
	ds_read_b128 v[182:185], v148
	ds_read_b128 v[186:189], v148 offset:1024
	ds_read_b128 v[190:193], v148 offset:2048
	ds_read_b128 v[198:201], v148 offset:3072
	ds_read_b128 v[202:205], v148 offset:4096
	ds_read_b128 v[206:209], v148 offset:5120
	ds_read_b128 v[210:213], v148 offset:6144
	ds_read_b128 v[214:217], v148 offset:7168
	global_load_lds_dwordx4 v[144:145], off
	v_lshl_add_u64 v[144:145], s[10:11], 0, v[142:143]
	s_add_i32 m0, s18, 0xe000
	s_nop 0
	global_load_lds_dwordx4 v[144:145], off
	s_nop 0
	s_waitcnt vmcnt(8)
	s_waitcnt lgkmcnt(0)
	s_barrier
	v_mfma_f32_16x16x32_bf16 v[130:133], v[150:153], v[182:185], v[130:133]
	v_mfma_f32_16x16x32_bf16 v[130:133], v[154:157], v[186:189], v[130:133]
	v_mfma_f32_16x16x32_bf16 v[114:117], v[150:153], v[190:193], v[114:117]
	v_mfma_f32_16x16x32_bf16 v[114:117], v[154:157], v[198:201], v[114:117]
	v_mfma_f32_16x16x32_bf16 v[98:101], v[150:153], v[202:205], v[98:101]
	v_mfma_f32_16x16x32_bf16 v[98:101], v[154:157], v[206:209], v[98:101]
	v_mfma_f32_16x16x32_bf16 v[82:85], v[150:153], v[210:213], v[82:85]
	v_mfma_f32_16x16x32_bf16 v[82:85], v[154:157], v[214:217], v[82:85]
	v_mfma_f32_16x16x32_bf16 v[126:129], v[158:161], v[182:185], v[126:129]
	v_mfma_f32_16x16x32_bf16 v[126:129], v[162:165], v[186:189], v[126:129]
	v_mfma_f32_16x16x32_bf16 v[106:109], v[158:161], v[190:193], v[106:109]
	v_mfma_f32_16x16x32_bf16 v[106:109], v[162:165], v[198:201], v[106:109]
	v_mfma_f32_16x16x32_bf16 v[94:97], v[158:161], v[202:205], v[94:97]
	v_mfma_f32_16x16x32_bf16 v[94:97], v[162:165], v[206:209], v[94:97]
	v_mfma_f32_16x16x32_bf16 v[78:81], v[158:161], v[210:213], v[78:81]
	v_mfma_f32_16x16x32_bf16 v[78:81], v[162:165], v[214:217], v[78:81]
	v_mfma_f32_16x16x32_bf16 v[122:125], v[166:169], v[182:185], v[122:125]
	v_mfma_f32_16x16x32_bf16 v[122:125], v[170:173], v[186:189], v[122:125]
	v_mfma_f32_16x16x32_bf16 v[110:113], v[166:169], v[190:193], v[110:113]
	v_mfma_f32_16x16x32_bf16 v[110:113], v[170:173], v[198:201], v[110:113]
	v_mfma_f32_16x16x32_bf16 v[90:93], v[166:169], v[202:205], v[90:93]
	v_mfma_f32_16x16x32_bf16 v[90:93], v[170:173], v[206:209], v[90:93]
	v_mfma_f32_16x16x32_bf16 v[74:77], v[166:169], v[210:213], v[74:77]
	v_mfma_f32_16x16x32_bf16 v[74:77], v[170:173], v[214:217], v[74:77]
	v_mfma_f32_16x16x32_bf16 v[118:121], v[174:177], v[182:185], v[118:121]
	v_mfma_f32_16x16x32_bf16 v[118:121], v[178:181], v[186:189], v[118:121]
	v_mfma_f32_16x16x32_bf16 v[102:105], v[174:177], v[190:193], v[102:105]
	v_mfma_f32_16x16x32_bf16 v[102:105], v[178:181], v[198:201], v[102:105]
	v_mfma_f32_16x16x32_bf16 v[86:89], v[174:177], v[202:205], v[86:89]
	v_mfma_f32_16x16x32_bf16 v[86:89], v[178:181], v[206:209], v[86:89]
	v_mfma_f32_16x16x32_bf16 v[70:73], v[174:177], v[210:213], v[70:73]
	v_mfma_f32_16x16x32_bf16 v[70:73], v[178:181], v[214:217], v[70:73]
	s_barrier
	s_add_i32 s46, s46, s17
	v_lshl_add_u64 v[144:145], s[12:13], 0, v[136:137]
	s_mov_b32 m0, s46
	ds_read_b128 v[182:185], v148 offset:16384
	ds_read_b128 v[186:189], v148 offset:17408
	ds_read_b128 v[190:193], v148 offset:18432
	ds_read_b128 v[198:201], v148 offset:19456
	ds_read_b128 v[202:205], v148 offset:20480
	ds_read_b128 v[206:209], v148 offset:21504
	ds_read_b128 v[210:213], v148 offset:22528
	ds_read_b128 v[214:217], v148 offset:23552
	global_load_lds_dwordx4 v[144:145], off
	s_add_i32 m0, s46, 0x2000
	s_add_u32 s46, s12, 0x40000
	v_lshl_add_u64 v[218:219], s[12:13], 0, v[2:3]
	s_addc_u32 s47, s13, 0
	s_add_i32 s48, s48, s17
	global_load_lds_dwordx4 v[218:219], off
	v_lshl_add_u64 v[220:221], s[46:47], 0, v[136:137]
	s_mov_b32 m0, s48
	v_lshl_add_u64 v[222:223], s[14:15], 0, v[134:135]
	global_load_lds_dwordx4 v[220:221], off
	v_lshl_add_u64 v[220:221], s[46:47], 0, v[2:3]
	s_add_i32 m0, s48, 0x2000
	s_nop 0
	global_load_lds_dwordx4 v[220:221], off
	v_lshl_add_u64 v[220:221], s[14:15], 0, v[138:139]
	s_mov_b32 m0, s18
	s_nop 0
	global_load_lds_dwordx4 v[220:221], off
	s_mov_b32 m0, s19
	s_nop 0
	global_load_lds_dwordx4 v[222:223], off
	s_waitcnt vmcnt(8)
	s_waitcnt lgkmcnt(0)
	s_barrier
; #define PG8_STAGE(bufoff, gbase, voff) do { _Pragma("unroll") for (int _i = 0; _i < 2; ++_i) \
;         __builtin_amdgcn_global_load_lds((const unsigned*)((const char*)(gbase) + (voff)[_i]), (PG8_LAS unsigned*)(lds + (bufoff) + ldsw + _i * 8192), 16, 0, 0); } while (0)
; #define PG8_LDA(dst, b, h) do { _Pragma("unroll") for (int m = 0; m < 4; ++m) _Pragma("unroll") for (int k = 0; k < 2; ++k) dst[m][k] = *(const PG8_LAS bf16x8*)(lds + PG8_SA(b, h) + aoff + m * 2048 + k * 1024); } while (0)
; #define PG8_LDB(dst, b, h) do { _Pragma("unroll") for (int n = 0; n < 2; ++n) _Pragma("unroll") for (int k = 0; k < 2; ++k) dst[n][k] = *(const PG8_LAS bf16x8*)(lds + PG8_SB(b, h) + boff + n * 2048 + k * 1024); } while (0)
; #define PG8_MMA(ai, bj, At, Bt) do { __builtin_amdgcn_s_setprio(1); _Pragma("unroll") for (int m = 0; m < 4; ++m) _Pragma("unroll") for (int n = 0; n < 2; ++n) _Pragma("unroll") for (int k = 0; k < 2; ++k) \
;         acc[ai][bj][m][n] = __builtin_amdgcn_mfma_f32_16x16x32_bf16(Bt[n][k], At[m][k], acc[ai][bj][m][n], 0, 0, 0); __builtin_amdgcn_s_setprio(0); } while (0)
; #define PG8_WAIT_V(n) asm volatile("s_waitcnt vmcnt(" #n ")" ::: "memory")
; #define PG8_WAIT_L(n) asm volatile("s_waitcnt lgkmcnt(" #n ")" ::: "memory")
; #define PG8_BAR __builtin_amdgcn_s_barrier()
; #define PG8_SCHED __builtin_amdgcn_sched_barrier(0)
; template <class Epi, class Sched, bool ALIGN_EPI = false, bool SP2 = false>
; __device__ __forceinline__ void gemm_phase(PG8_LAS unsigned char* lds, const Gemm g, const Sched& S, const Epi& E, const int tid_in) {
;     ...
;             PG8_WAIT_V(8); PG8_WAIT_L(0); PG8_BAR; PG8_MMA(1, 0, At, B0); PG8_MMA(1, 1, At, B1); PG8_BAR; PG8_SCHED;
;             PG8_LDB(B0, 1, 0); PG8_LDB(B1, 1, 1); PG8_SCHED; PG8_LDA(At, 1, 0); PG8_STAGE(PG8_SA(0, 1), a2 + hstep, voffA);
	v_mfma_f32_16x16x32_bf16 v[66:69], v[150:153], v[182:185], v[66:69]
	v_mfma_f32_16x16x32_bf16 v[66:69], v[154:157], v[186:189], v[66:69]
	v_mfma_f32_16x16x32_bf16 v[50:53], v[150:153], v[190:193], v[50:53]
	v_mfma_f32_16x16x32_bf16 v[50:53], v[154:157], v[198:201], v[50:53]
	v_mfma_f32_16x16x32_bf16 v[34:37], v[150:153], v[202:205], v[34:37]
	v_mfma_f32_16x16x32_bf16 v[34:37], v[154:157], v[206:209], v[34:37]
	v_mfma_f32_16x16x32_bf16 v[18:21], v[150:153], v[210:213], v[18:21]
	v_mfma_f32_16x16x32_bf16 v[18:21], v[154:157], v[214:217], v[18:21]
	v_mfma_f32_16x16x32_bf16 v[62:65], v[158:161], v[182:185], v[62:65]
	v_mfma_f32_16x16x32_bf16 v[62:65], v[162:165], v[186:189], v[62:65]
	v_mfma_f32_16x16x32_bf16 v[46:49], v[158:161], v[190:193], v[46:49]
	v_mfma_f32_16x16x32_bf16 v[46:49], v[162:165], v[198:201], v[46:49]
	v_mfma_f32_16x16x32_bf16 v[30:33], v[158:161], v[202:205], v[30:33]
	v_mfma_f32_16x16x32_bf16 v[30:33], v[162:165], v[206:209], v[30:33]
	v_mfma_f32_16x16x32_bf16 v[14:17], v[158:161], v[210:213], v[14:17]
	v_mfma_f32_16x16x32_bf16 v[14:17], v[162:165], v[214:217], v[14:17]
	v_mfma_f32_16x16x32_bf16 v[58:61], v[166:169], v[182:185], v[58:61]
	v_mfma_f32_16x16x32_bf16 v[58:61], v[170:173], v[186:189], v[58:61]
	v_mfma_f32_16x16x32_bf16 v[42:45], v[166:169], v[190:193], v[42:45]
	v_mfma_f32_16x16x32_bf16 v[42:45], v[170:173], v[198:201], v[42:45]
	v_mfma_f32_16x16x32_bf16 v[26:29], v[166:169], v[202:205], v[26:29]
	v_mfma_f32_16x16x32_bf16 v[26:29], v[170:173], v[206:209], v[26:29]
	v_mfma_f32_16x16x32_bf16 v[10:13], v[166:169], v[210:213], v[10:13]
	v_mfma_f32_16x16x32_bf16 v[10:13], v[170:173], v[214:217], v[10:13]
	v_mfma_f32_16x16x32_bf16 v[54:57], v[174:177], v[182:185], v[54:57]
	v_mfma_f32_16x16x32_bf16 v[54:57], v[178:181], v[186:189], v[54:57]
	v_mfma_f32_16x16x32_bf16 v[38:41], v[174:177], v[190:193], v[38:41]
	v_mfma_f32_16x16x32_bf16 v[38:41], v[178:181], v[198:201], v[38:41]
	v_mfma_f32_16x16x32_bf16 v[22:25], v[174:177], v[202:205], v[22:25]
	v_mfma_f32_16x16x32_bf16 v[22:25], v[178:181], v[206:209], v[22:25]
	v_mfma_f32_16x16x32_bf16 v[6:9], v[174:177], v[210:213], v[6:9]
	v_mfma_f32_16x16x32_bf16 v[6:9], v[178:181], v[214:217], v[6:9]
	s_barrier
	s_add_i32 s46, 0, 0x18000
	v_add_u32_e32 v149, s46, v146
	s_add_i32 s47, 0, 0x1c000
	ds_read_b128 v[150:153], v149
	ds_read_b128 v[154:157], v149 offset:1024
	ds_read_b128 v[158:161], v149 offset:2048
	ds_read_b128 v[162:165], v149 offset:3072
	v_add_u32_e32 v149, s47, v146
	ds_read_b128 v[166:169], v149
	ds_read_b128 v[170:173], v149 offset:1024
	ds_read_b128 v[174:177], v149 offset:2048
	ds_read_b128 v[178:181], v149 offset:3072
	s_add_u32 s14, s14, 0x40000
	s_addc_u32 s15, s15, 0
	s_mov_b32 m0, s22
	v_lshl_add_u64 v[224:225], s[14:15], 0, v[138:139]
	ds_read_b128 v[182:185], v148 offset:32768
	ds_read_b128 v[186:189], v148 offset:33792
	ds_read_b128 v[190:193], v148 offset:34816
	ds_read_b128 v[198:201], v148 offset:35840
	ds_read_b128 v[202:205], v148 offset:36864
	ds_read_b128 v[206:209], v148 offset:37888
	ds_read_b128 v[210:213], v148 offset:38912
	ds_read_b128 v[214:217], v148 offset:39936
	global_load_lds_dwordx4 v[224:225], off
	v_lshl_add_u64 v[224:225], s[14:15], 0, v[134:135]
	s_mov_b32 m0, s23
	s_nop 0
	global_load_lds_dwordx4 v[224:225], off
	s_waitcnt vmcnt(8)
	s_waitcnt lgkmcnt(0)
	s_barrier
; #define PG8_STAGE(bufoff, gbase, voff) do { _Pragma("unroll") for (int _i = 0; _i < 2; ++_i) \
;         __builtin_amdgcn_global_load_lds((const unsigned*)((const char*)(gbase) + (voff)[_i]), (PG8_LAS unsigned*)(lds + (bufoff) + ldsw + _i * 8192), 16, 0, 0); } while (0)
; #define PG8_LDA(dst, b, h) do { _Pragma("unroll") for (int m = 0; m < 4; ++m) _Pragma("unroll") for (int k = 0; k < 2; ++k) dst[m][k] = *(const PG8_LAS bf16x8*)(lds + PG8_SA(b, h) + aoff + m * 2048 + k * 1024); } while (0)
; #define PG8_MMA(ai, bj, At, Bt) do { __builtin_amdgcn_s_setprio(1); _Pragma("unroll") for (int m = 0; m < 4; ++m) _Pragma("unroll") for (int n = 0; n < 2; ++n) _Pragma("unroll") for (int k = 0; k < 2; ++k) \
;         acc[ai][bj][m][n] = __builtin_amdgcn_mfma_f32_16x16x32_bf16(Bt[n][k], At[m][k], acc[ai][bj][m][n], 0, 0, 0); __builtin_amdgcn_s_setprio(0); } while (0)
; #define PG8_WAIT_V(n) asm volatile("s_waitcnt vmcnt(" #n ")" ::: "memory")
; #define PG8_WAIT_L(n) asm volatile("s_waitcnt lgkmcnt(" #n ")" ::: "memory")
; #define PG8_BAR __builtin_amdgcn_s_barrier()
; #define PG8_SCHED __builtin_amdgcn_sched_barrier(0)
; template <class Epi, class Sched, bool ALIGN_EPI = false, bool SP2 = false>
; __device__ __forceinline__ void gemm_phase(PG8_LAS unsigned char* lds, const Gemm g, const Sched& S, const Epi& E, const int tid_in) {
;     ...
;             PG8_WAIT_V(8); PG8_WAIT_L(0); PG8_BAR; PG8_MMA(0, 0, At, B0); PG8_MMA(0, 1, At, B1); PG8_BAR; PG8_SCHED;
;             PG8_LDA(At, 1, 1); PG8_STAGE(PG8_SB(1, 0), b3, voffB); PG8_STAGE(PG8_SB(1, 1), b3 + hstep, voffB); PG8_STAGE(PG8_SA(1, 0), a3, voffA);
;             PG8_WAIT_V(8); PG8_WAIT_L(0); PG8_BAR; PG8_MMA(1, 0, At, B0); PG8_MMA(1, 1, At, B1); PG8_BAR; PG8_SCHED;
;     __device__ __forceinline__ void operator()(const f32x4 (&acc)[2][2][4][2], const Unit& u, int wr, int wc, int fr, int fq) const {
;     ...
;             for (int m = 0; m < 4; ++m) rs[ai][m] = rowss[row0 + ai * HALF + m * 16];
	v_mfma_f32_16x16x32_bf16 v[130:133], v[150:153], v[182:185], v[130:133]
	v_mfma_f32_16x16x32_bf16 v[130:133], v[154:157], v[186:189], v[130:133]
	v_mfma_f32_16x16x32_bf16 v[114:117], v[150:153], v[190:193], v[114:117]
	v_mfma_f32_16x16x32_bf16 v[114:117], v[154:157], v[198:201], v[114:117]
	v_mfma_f32_16x16x32_bf16 v[98:101], v[150:153], v[202:205], v[98:101]
	v_mfma_f32_16x16x32_bf16 v[98:101], v[154:157], v[206:209], v[98:101]
	v_mfma_f32_16x16x32_bf16 v[82:85], v[150:153], v[210:213], v[82:85]
	v_mfma_f32_16x16x32_bf16 v[82:85], v[154:157], v[214:217], v[82:85]
	v_mfma_f32_16x16x32_bf16 v[126:129], v[158:161], v[182:185], v[126:129]
	v_mfma_f32_16x16x32_bf16 v[126:129], v[162:165], v[186:189], v[126:129]
	v_mfma_f32_16x16x32_bf16 v[106:109], v[158:161], v[190:193], v[106:109]
	v_mfma_f32_16x16x32_bf16 v[106:109], v[162:165], v[198:201], v[106:109]
	v_mfma_f32_16x16x32_bf16 v[94:97], v[158:161], v[202:205], v[94:97]
	v_mfma_f32_16x16x32_bf16 v[94:97], v[162:165], v[206:209], v[94:97]
	v_mfma_f32_16x16x32_bf16 v[78:81], v[158:161], v[210:213], v[78:81]
	v_mfma_f32_16x16x32_bf16 v[78:81], v[162:165], v[214:217], v[78:81]
	v_mfma_f32_16x16x32_bf16 v[122:125], v[166:169], v[182:185], v[122:125]
	v_mfma_f32_16x16x32_bf16 v[122:125], v[170:173], v[186:189], v[122:125]
	v_mfma_f32_16x16x32_bf16 v[110:113], v[166:169], v[190:193], v[110:113]
	v_mfma_f32_16x16x32_bf16 v[110:113], v[170:173], v[198:201], v[110:113]
	v_mfma_f32_16x16x32_bf16 v[90:93], v[166:169], v[202:205], v[90:93]
	v_mfma_f32_16x16x32_bf16 v[90:93], v[170:173], v[206:209], v[90:93]
	v_mfma_f32_16x16x32_bf16 v[74:77], v[166:169], v[210:213], v[74:77]
	v_mfma_f32_16x16x32_bf16 v[74:77], v[170:173], v[214:217], v[74:77]
	v_mfma_f32_16x16x32_bf16 v[118:121], v[174:177], v[182:185], v[118:121]
	v_mfma_f32_16x16x32_bf16 v[118:121], v[178:181], v[186:189], v[118:121]
	v_mfma_f32_16x16x32_bf16 v[102:105], v[174:177], v[190:193], v[102:105]
	v_mfma_f32_16x16x32_bf16 v[102:105], v[178:181], v[198:201], v[102:105]
	v_mfma_f32_16x16x32_bf16 v[86:89], v[174:177], v[202:205], v[86:89]
	v_mfma_f32_16x16x32_bf16 v[86:89], v[178:181], v[206:209], v[86:89]
	v_mfma_f32_16x16x32_bf16 v[70:73], v[174:177], v[210:213], v[70:73]
	v_mfma_f32_16x16x32_bf16 v[70:73], v[178:181], v[214:217], v[70:73]
	s_barrier
	s_add_i32 s14, s46, s17
	v_lshl_add_u64 v[144:145], v[144:145], 0, s[28:29]
	s_mov_b32 m0, s14
	ds_read_b128 v[182:185], v148 offset:49152
	ds_read_b128 v[186:189], v148 offset:50176
	ds_read_b128 v[190:193], v148 offset:51200
	ds_read_b128 v[198:201], v148 offset:52224
	ds_read_b128 v[202:205], v148 offset:53248
	ds_read_b128 v[206:209], v148 offset:54272
	ds_read_b128 v[210:213], v148 offset:55296
	ds_read_b128 v[214:217], v148 offset:56320
	global_load_lds_dwordx4 v[144:145], off
	s_add_i32 m0, s14, 0x2000
	s_add_u32 s12, s12, 0x40080
	v_lshl_add_u64 v[144:145], v[218:219], 0, s[28:29]
	s_addc_u32 s13, s13, 0
	s_add_i32 s14, s47, s17
	global_load_lds_dwordx4 v[144:145], off
	v_lshl_add_u64 v[144:145], s[12:13], 0, v[136:137]
	s_mov_b32 m0, s14
	s_nop 0
	global_load_lds_dwordx4 v[144:145], off
	v_lshl_add_u64 v[144:145], s[12:13], 0, v[2:3]
	s_add_i32 m0, s14, 0x2000
	s_nop 0
	global_load_lds_dwordx4 v[144:145], off
	v_lshl_add_u64 v[144:145], v[220:221], 0, s[28:29]
	s_mov_b32 m0, s26
	s_nop 0
	global_load_lds_dwordx4 v[144:145], off
	v_lshl_add_u64 v[144:145], v[222:223], 0, s[28:29]
	s_mov_b32 m0, s27
	s_nop 0
	global_load_lds_dwordx4 v[144:145], off
	s_waitcnt vmcnt(8)
	s_waitcnt lgkmcnt(0)
	s_cmp_lg_u32 s45, 12
	s_cbranch_scc1 .Lrs_gu_skip
	v_lshl_add_u32 v144, s40, 8, v5
	v_ashrrev_i32_e32 v145, 31, v144
	v_lshl_add_u64 v[144:145], v[144:145], 2, s[6:7]
	global_load_dword v226, v[144:145], off
	global_load_dword v227, v[144:145], off offset:64
	global_load_dword v228, v[144:145], off offset:128
	global_load_dword v229, v[144:145], off offset:192
	global_load_dword v238, v[144:145], off offset:512
	global_load_dword v239, v[144:145], off offset:576
	global_load_dword v240, v[144:145], off offset:640
	global_load_dword v241, v[144:145], off offset:704

; #define PG8_STAGE(bufoff, gbase, voff) do { _Pragma("unroll") for (int _i = 0; _i < 2; ++_i) \
;         __builtin_amdgcn_global_load_lds((const unsigned*)((const char*)(gbase) + (voff)[_i]), (PG8_LAS unsigned*)(lds + (bufoff) + ldsw + _i * 8192), 16, 0, 0); } while (0)
; #define PG8_LDA(dst, b, h) do { _Pragma("unroll") for (int m = 0; m < 4; ++m) _Pragma("unroll") for (int k = 0; k < 2; ++k) dst[m][k] = *(const PG8_LAS bf16x8*)(lds + PG8_SA(b, h) + aoff + m * 2048 + k * 1024); } while (0)
; #define PG8_LDB(dst, b, h) do { _Pragma("unroll") for (int n = 0; n < 2; ++n) _Pragma("unroll") for (int k = 0; k < 2; ++k) dst[n][k] = *(const PG8_LAS bf16x8*)(lds + PG8_SB(b, h) + boff + n * 2048 + k * 1024); } while (0)
; #define PG8_MMA(ai, bj, At, Bt) do { __builtin_amdgcn_s_setprio(1); _Pragma("unroll") for (int m = 0; m < 4; ++m) _Pragma("unroll") for (int n = 0; n < 2; ++n) _Pragma("unroll") for (int k = 0; k < 2; ++k) \
;         acc[ai][bj][m][n] = __builtin_amdgcn_mfma_f32_16x16x32_bf16(Bt[n][k], At[m][k], acc[ai][bj][m][n], 0, 0, 0); __builtin_amdgcn_s_setprio(0); } while (0)
; #define PG8_WAIT_V(n) asm volatile("s_waitcnt vmcnt(" #n ")" ::: "memory")
; #define PG8_WAIT_L(n) asm volatile("s_waitcnt lgkmcnt(" #n ")" ::: "memory")
; #define PG8_BAR __builtin_amdgcn_s_barrier()
; #define PG8_SCHED __builtin_amdgcn_sched_barrier(0)
; template <class Epi, class Sched, bool ALIGN_EPI = false, bool SP2 = false>
; __device__ __forceinline__ void gemm_phase(PG8_LAS unsigned char* lds, const Gemm g, const Sched& S, const Epi& E, const int tid_in) {
;     ...
;             PG8_LDB(B0, 0, 0); PG8_LDB(B1, 0, 1); PG8_SCHED; PG8_LDA(At, 0, 0); PG8_STAGE(PG8_SA(1, 1), a1 + hstep, voffA);
;             PG8_WAIT_V(8); PG8_WAIT_L(0); PG8_BAR; PG8_MMA(0, 0, At, B0); PG8_MMA(0, 1, At, B1); PG8_BAR; PG8_SCHED;
;             PG8_LDA(At, 0, 1); PG8_STAGE(PG8_SB(0, 0), b2, voffB); PG8_STAGE(PG8_SB(0, 1), b2 + hstep, voffB); PG8_STAGE(PG8_SA(0, 0), a2, voffA);
;     ...
;         for (int a = 0; a < 2; ++a)
; #pragma unroll
;             for (int b = 0; b < 2; ++b)
; #pragma unroll
;                 for (int m = 0; m < 4; ++m)
; #pragma unroll
;                     for (int n = 0; n < 2; ++n) acc[a][b][m][n] = (f32x4){0.f, 0.f, 0.f, 0.f};
.LBB0_176:
	s_add_u32 s10, s10, 0x80
	s_addc_u32 s11, s11, 0
	s_add_u32 s14, s12, 0x100
	s_addc_u32 s15, s13, 0
	s_mov_b32 s12, 0
	s_waitcnt lgkmcnt(0)
	s_add_i32 s51, s12, 2
	s_add_u32 s52, s10, 0x80
	s_addc_u32 s13, s11, 0
	s_add_i32 s54, 0, 0x10000
	s_cmp_eq_u32 s31, s12
	s_cselect_b32 s13, s1, s13
	s_cselect_b32 s12, s0, s52
	s_cselect_b32 s53, s45, s15
	s_cselect_b32 s52, s44, s14
	s_add_i32 s55, 0, 0x14000
	v_add_u32_e32 v138, s54, v247
	v_add_u32_e32 v154, s55, v247
	ds_read_b128 v[126:129], v138
	ds_read_b128 v[130:133], v138 offset:1024
	ds_read_b128 v[134:137], v138 offset:2048
	ds_read_b128 v[138:141], v138 offset:3072
	ds_read_b128 v[142:145], v154
	ds_read_b128 v[146:149], v154 offset:1024
	ds_read_b128 v[150:153], v154 offset:2048
	ds_read_b128 v[154:157], v154 offset:3072
	v_lshl_add_u64 v[214:215], s[10:11], 0, v[206:207]
	s_add_i32 m0, s18, 0xc000
	ds_read_b128 v[158:161], v249
	ds_read_b128 v[162:165], v249 offset:1024
	ds_read_b128 v[170:173], v249 offset:2048
	ds_read_b128 v[178:181], v249 offset:3072
	ds_read_b128 v[182:185], v249 offset:4096
	ds_read_b128 v[186:189], v249 offset:5120
	ds_read_b128 v[190:193], v249 offset:6144
	ds_read_b128 v[210:213], v249 offset:7168
	global_load_lds_dwordx4 v[214:215], off
	v_lshl_add_u64 v[214:215], s[10:11], 0, v[208:209]
	s_add_i32 m0, s18, 0xe000
	s_nop 0
	global_load_lds_dwordx4 v[214:215], off
	s_waitcnt vmcnt(8)
	s_waitcnt lgkmcnt(0)
	s_barrier
	v_mfma_f32_16x16x32_bf16 v[174:177], v[126:129], v[158:161], 0
	v_mfma_f32_16x16x32_bf16 v[174:177], v[130:133], v[162:165], v[174:177]
	v_mfma_f32_16x16x32_bf16 v[114:117], v[126:129], v[170:173], 0
	v_mfma_f32_16x16x32_bf16 v[114:117], v[130:133], v[178:181], v[114:117]
	v_mfma_f32_16x16x32_bf16 v[98:101], v[126:129], v[182:185], 0
	v_mfma_f32_16x16x32_bf16 v[98:101], v[130:133], v[186:189], v[98:101]
	v_mfma_f32_16x16x32_bf16 v[82:85], v[126:129], v[190:193], 0
	v_mfma_f32_16x16x32_bf16 v[82:85], v[130:133], v[210:213], v[82:85]
	v_mfma_f32_16x16x32_bf16 v[166:169], v[134:137], v[158:161], 0
	v_mfma_f32_16x16x32_bf16 v[166:169], v[138:141], v[162:165], v[166:169]
	v_mfma_f32_16x16x32_bf16 v[110:113], v[134:137], v[170:173], 0
	v_mfma_f32_16x16x32_bf16 v[110:113], v[138:141], v[178:181], v[110:113]
	v_mfma_f32_16x16x32_bf16 v[94:97], v[134:137], v[182:185], 0
	v_mfma_f32_16x16x32_bf16 v[94:97], v[138:141], v[186:189], v[94:97]
	v_mfma_f32_16x16x32_bf16 v[78:81], v[134:137], v[190:193], 0
	v_mfma_f32_16x16x32_bf16 v[78:81], v[138:141], v[210:213], v[78:81]
	v_mfma_f32_16x16x32_bf16 v[122:125], v[142:145], v[158:161], 0
	v_mfma_f32_16x16x32_bf16 v[122:125], v[146:149], v[162:165], v[122:125]
	v_mfma_f32_16x16x32_bf16 v[106:109], v[142:145], v[170:173], 0
	v_mfma_f32_16x16x32_bf16 v[106:109], v[146:149], v[178:181], v[106:109]
	v_mfma_f32_16x16x32_bf16 v[90:93], v[142:145], v[182:185], 0
	v_mfma_f32_16x16x32_bf16 v[90:93], v[146:149], v[186:189], v[90:93]
	v_mfma_f32_16x16x32_bf16 v[74:77], v[142:145], v[190:193], 0
	v_mfma_f32_16x16x32_bf16 v[74:77], v[146:149], v[210:213], v[74:77]
	v_mfma_f32_16x16x32_bf16 v[118:121], v[150:153], v[158:161], 0
	v_mfma_f32_16x16x32_bf16 v[118:121], v[154:157], v[162:165], v[118:121]
	v_mfma_f32_16x16x32_bf16 v[102:105], v[150:153], v[170:173], 0
	v_mfma_f32_16x16x32_bf16 v[102:105], v[154:157], v[178:181], v[102:105]
	v_mfma_f32_16x16x32_bf16 v[86:89], v[150:153], v[182:185], 0
	v_mfma_f32_16x16x32_bf16 v[86:89], v[154:157], v[186:189], v[86:89]
	v_mfma_f32_16x16x32_bf16 v[70:73], v[150:153], v[190:193], 0
	v_mfma_f32_16x16x32_bf16 v[70:73], v[154:157], v[210:213], v[70:73]
	s_barrier
	s_add_i32 s54, s54, s17
	v_lshl_add_u64 v[214:215], s[52:53], 0, v[202:203]
	s_mov_b32 m0, s54
	ds_read_b128 v[158:161], v249 offset:16384
	ds_read_b128 v[162:165], v249 offset:17408
	ds_read_b128 v[170:173], v249 offset:18432
	ds_read_b128 v[178:181], v249 offset:19456
	ds_read_b128 v[182:185], v249 offset:20480
	ds_read_b128 v[186:189], v249 offset:21504
	ds_read_b128 v[190:193], v249 offset:22528
	ds_read_b128 v[210:213], v249 offset:23552
	global_load_lds_dwordx4 v[214:215], off
	s_add_i32 m0, s54, 0x2000
	v_lshl_add_u64 v[216:217], s[52:53], 0, v[198:199]
	s_add_u32 s52, s52, s62
	s_addc_u32 s53, s53, 0
	s_add_i32 s54, s55, s17
	global_load_lds_dwordx4 v[216:217], off
	v_lshl_add_u64 v[218:219], s[52:53], 0, v[202:203]
	s_mov_b32 m0, s54
	v_lshl_add_u64 v[220:221], s[52:53], 0, v[198:199]
	global_load_lds_dwordx4 v[218:219], off
	s_add_i32 m0, s54, 0x2000
	v_lshl_add_u64 v[222:223], s[12:13], 0, v[204:205]
	global_load_lds_dwordx4 v[220:221], off
	s_mov_b32 m0, s18
	v_lshl_add_u64 v[224:225], s[12:13], 0, v[200:201]
	global_load_lds_dwordx4 v[222:223], off
	s_mov_b32 m0, s19
	s_nop 0
	global_load_lds_dwordx4 v[224:225], off
	s_nop 0
	s_waitcnt vmcnt(8)
	s_waitcnt lgkmcnt(0)
	s_barrier
; #define PG8_STAGE(bufoff, gbase, voff) do { _Pragma("unroll") for (int _i = 0; _i < 2; ++_i) \
;         __builtin_amdgcn_global_load_lds((const unsigned*)((const char*)(gbase) + (voff)[_i]), (PG8_LAS unsigned*)(lds + (bufoff) + ldsw + _i * 8192), 16, 0, 0); } while (0)
; #define PG8_LDA(dst, b, h) do { _Pragma("unroll") for (int m = 0; m < 4; ++m) _Pragma("unroll") for (int k = 0; k < 2; ++k) dst[m][k] = *(const PG8_LAS bf16x8*)(lds + PG8_SA(b, h) + aoff + m * 2048 + k * 1024); } while (0)
; #define PG8_LDB(dst, b, h) do { _Pragma("unroll") for (int n = 0; n < 2; ++n) _Pragma("unroll") for (int k = 0; k < 2; ++k) dst[n][k] = *(const PG8_LAS bf16x8*)(lds + PG8_SB(b, h) + boff + n * 2048 + k * 1024); } while (0)
; #define PG8_MMA(ai, bj, At, Bt) do { __builtin_amdgcn_s_setprio(1); _Pragma("unroll") for (int m = 0; m < 4; ++m) _Pragma("unroll") for (int n = 0; n < 2; ++n) _Pragma("unroll") for (int k = 0; k < 2; ++k) \
;         acc[ai][bj][m][n] = __builtin_amdgcn_mfma_f32_16x16x32_bf16(Bt[n][k], At[m][k], acc[ai][bj][m][n], 0, 0, 0); __builtin_amdgcn_s_setprio(0); } while (0)
; #define PG8_WAIT_V(n) asm volatile("s_waitcnt vmcnt(" #n ")" ::: "memory")
; #define PG8_WAIT_L(n) asm volatile("s_waitcnt lgkmcnt(" #n ")" ::: "memory")
; #define PG8_BAR __builtin_amdgcn_s_barrier()
; #define PG8_SCHED __builtin_amdgcn_sched_barrier(0)
; template <class Epi, class Sched, bool ALIGN_EPI = false, bool SP2 = false>
; __device__ __forceinline__ void gemm_phase(PG8_LAS unsigned char* lds, const Gemm g, const Sched& S, const Epi& E, const int tid_in) {
;     ...
;             PG8_WAIT_V(8); PG8_WAIT_L(0); PG8_BAR; PG8_MMA(1, 0, At, B0); PG8_MMA(1, 1, At, B1); PG8_BAR; PG8_SCHED;
;             PG8_LDB(B0, 1, 0); PG8_LDB(B1, 1, 1); PG8_SCHED; PG8_LDA(At, 1, 0); PG8_STAGE(PG8_SA(0, 1), a2 + hstep, voffA);
;             PG8_WAIT_V(8); PG8_WAIT_L(0); PG8_BAR; PG8_MMA(0, 0, At, B0); PG8_MMA(0, 1, At, B1); PG8_BAR; PG8_SCHED;
	v_mfma_f32_16x16x32_bf16 v[66:69], v[126:129], v[158:161], 0
	v_mfma_f32_16x16x32_bf16 v[66:69], v[130:133], v[162:165], v[66:69]
	v_mfma_f32_16x16x32_bf16 v[50:53], v[126:129], v[170:173], 0
	v_mfma_f32_16x16x32_bf16 v[50:53], v[130:133], v[178:181], v[50:53]
	v_mfma_f32_16x16x32_bf16 v[34:37], v[126:129], v[182:185], 0
	v_mfma_f32_16x16x32_bf16 v[34:37], v[130:133], v[186:189], v[34:37]
	v_mfma_f32_16x16x32_bf16 v[18:21], v[126:129], v[190:193], 0
	v_mfma_f32_16x16x32_bf16 v[18:21], v[130:133], v[210:213], v[18:21]
	v_mfma_f32_16x16x32_bf16 v[62:65], v[134:137], v[158:161], 0
	v_mfma_f32_16x16x32_bf16 v[62:65], v[138:141], v[162:165], v[62:65]
	v_mfma_f32_16x16x32_bf16 v[46:49], v[134:137], v[170:173], 0
	v_mfma_f32_16x16x32_bf16 v[46:49], v[138:141], v[178:181], v[46:49]
	v_mfma_f32_16x16x32_bf16 v[30:33], v[134:137], v[182:185], 0
	v_mfma_f32_16x16x32_bf16 v[30:33], v[138:141], v[186:189], v[30:33]
	v_mfma_f32_16x16x32_bf16 v[14:17], v[134:137], v[190:193], 0
	v_mfma_f32_16x16x32_bf16 v[14:17], v[138:141], v[210:213], v[14:17]
	v_mfma_f32_16x16x32_bf16 v[58:61], v[142:145], v[158:161], 0
	v_mfma_f32_16x16x32_bf16 v[58:61], v[146:149], v[162:165], v[58:61]
	v_mfma_f32_16x16x32_bf16 v[42:45], v[142:145], v[170:173], 0
	v_mfma_f32_16x16x32_bf16 v[42:45], v[146:149], v[178:181], v[42:45]
	v_mfma_f32_16x16x32_bf16 v[26:29], v[142:145], v[182:185], 0
	v_mfma_f32_16x16x32_bf16 v[26:29], v[146:149], v[186:189], v[26:29]
	v_mfma_f32_16x16x32_bf16 v[10:13], v[142:145], v[190:193], 0
	v_mfma_f32_16x16x32_bf16 v[10:13], v[146:149], v[210:213], v[10:13]
	v_mfma_f32_16x16x32_bf16 v[54:57], v[150:153], v[158:161], 0
	v_mfma_f32_16x16x32_bf16 v[54:57], v[154:157], v[162:165], v[54:57]
	v_mfma_f32_16x16x32_bf16 v[38:41], v[150:153], v[170:173], 0
	v_mfma_f32_16x16x32_bf16 v[38:41], v[154:157], v[178:181], v[38:41]
	v_mfma_f32_16x16x32_bf16 v[22:25], v[150:153], v[182:185], 0
	v_mfma_f32_16x16x32_bf16 v[22:25], v[154:157], v[186:189], v[22:25]
	v_mfma_f32_16x16x32_bf16 v[6:9], v[150:153], v[190:193], 0
	v_mfma_f32_16x16x32_bf16 v[6:9], v[154:157], v[210:213], v[6:9]
	s_barrier
	s_add_i32 s52, 0, 0x18000
	s_add_i32 s53, 0, 0x1c000
	v_add_u32_e32 v138, s52, v247
	v_add_u32_e32 v154, s53, v247
	ds_read_b128 v[126:129], v138
	ds_read_b128 v[130:133], v138 offset:1024
	ds_read_b128 v[134:137], v138 offset:2048
	ds_read_b128 v[138:141], v138 offset:3072
	ds_read_b128 v[142:145], v154
	ds_read_b128 v[146:149], v154 offset:1024
	ds_read_b128 v[150:153], v154 offset:2048
	ds_read_b128 v[154:157], v154 offset:3072
	s_add_u32 s12, s12, s62
	s_addc_u32 s13, s13, 0
	s_mov_b32 m0, s22
	v_lshl_add_u64 v[226:227], s[12:13], 0, v[204:205]
	ds_read_b128 v[158:161], v249 offset:32768
	ds_read_b128 v[162:165], v249 offset:33792
	ds_read_b128 v[170:173], v249 offset:34816
	ds_read_b128 v[178:181], v249 offset:35840
	ds_read_b128 v[182:185], v249 offset:36864
	ds_read_b128 v[186:189], v249 offset:37888
	ds_read_b128 v[190:193], v249 offset:38912
	ds_read_b128 v[210:213], v249 offset:39936
	global_load_lds_dwordx4 v[226:227], off
	v_lshl_add_u64 v[226:227], s[12:13], 0, v[200:201]
	s_mov_b32 m0, s23
	s_nop 0
	global_load_lds_dwordx4 v[226:227], off
	s_nop 0
	s_waitcnt vmcnt(8)
	s_waitcnt lgkmcnt(0)
	s_barrier
	v_mfma_f32_16x16x32_bf16 v[174:177], v[126:129], v[158:161], v[174:177]
	v_mfma_f32_16x16x32_bf16 v[174:177], v[130:133], v[162:165], v[174:177]
	v_mfma_f32_16x16x32_bf16 v[114:117], v[126:129], v[170:173], v[114:117]
	v_mfma_f32_16x16x32_bf16 v[114:117], v[130:133], v[178:181], v[114:117]
	v_mfma_f32_16x16x32_bf16 v[98:101], v[126:129], v[182:185], v[98:101]
	v_mfma_f32_16x16x32_bf16 v[98:101], v[130:133], v[186:189], v[98:101]
	v_mfma_f32_16x16x32_bf16 v[82:85], v[126:129], v[190:193], v[82:85]
	v_mfma_f32_16x16x32_bf16 v[82:85], v[130:133], v[210:213], v[82:85]
	v_mfma_f32_16x16x32_bf16 v[166:169], v[134:137], v[158:161], v[166:169]
	v_mfma_f32_16x16x32_bf16 v[166:169], v[138:141], v[162:165], v[166:169]
	v_mfma_f32_16x16x32_bf16 v[110:113], v[134:137], v[170:173], v[110:113]
	v_mfma_f32_16x16x32_bf16 v[110:113], v[138:141], v[178:181], v[110:113]
	v_mfma_f32_16x16x32_bf16 v[94:97], v[134:137], v[182:185], v[94:97]
	v_mfma_f32_16x16x32_bf16 v[94:97], v[138:141], v[186:189], v[94:97]
	v_mfma_f32_16x16x32_bf16 v[78:81], v[134:137], v[190:193], v[78:81]
	v_mfma_f32_16x16x32_bf16 v[78:81], v[138:141], v[210:213], v[78:81]
	v_mfma_f32_16x16x32_bf16 v[122:125], v[142:145], v[158:161], v[122:125]
	v_mfma_f32_16x16x32_bf16 v[122:125], v[146:149], v[162:165], v[122:125]
	v_mfma_f32_16x16x32_bf16 v[106:109], v[142:145], v[170:173], v[106:109]
	v_mfma_f32_16x16x32_bf16 v[106:109], v[146:149], v[178:181], v[106:109]
	v_mfma_f32_16x16x32_bf16 v[90:93], v[142:145], v[182:185], v[90:93]
	v_mfma_f32_16x16x32_bf16 v[90:93], v[146:149], v[186:189], v[90:93]
	v_mfma_f32_16x16x32_bf16 v[74:77], v[142:145], v[190:193], v[74:77]
	v_mfma_f32_16x16x32_bf16 v[74:77], v[146:149], v[210:213], v[74:77]
	v_mfma_f32_16x16x32_bf16 v[118:121], v[150:153], v[158:161], v[118:121]
	v_mfma_f32_16x16x32_bf16 v[118:121], v[154:157], v[162:165], v[118:121]
	v_mfma_f32_16x16x32_bf16 v[102:105], v[150:153], v[170:173], v[102:105]
	v_mfma_f32_16x16x32_bf16 v[102:105], v[154:157], v[178:181], v[102:105]
	v_mfma_f32_16x16x32_bf16 v[86:89], v[150:153], v[182:185], v[86:89]
	v_mfma_f32_16x16x32_bf16 v[86:89], v[154:157], v[186:189], v[86:89]
	v_mfma_f32_16x16x32_bf16 v[70:73], v[150:153], v[190:193], v[70:73]
	v_mfma_f32_16x16x32_bf16 v[70:73], v[154:157], v[210:213], v[70:73]
	s_barrier
; #define PG8_STAGE(bufoff, gbase, voff) do { _Pragma("unroll") for (int _i = 0; _i < 2; ++_i) \
;         __builtin_amdgcn_global_load_lds((const unsigned*)((const char*)(gbase) + (voff)[_i]), (PG8_LAS unsigned*)(lds + (bufoff) + ldsw + _i * 8192), 16, 0, 0); } while (0)
; #define PG8_LDA(dst, b, h) do { _Pragma("unroll") for (int m = 0; m < 4; ++m) _Pragma("unroll") for (int k = 0; k < 2; ++k) dst[m][k] = *(const PG8_LAS bf16x8*)(lds + PG8_SA(b, h) + aoff + m * 2048 + k * 1024); } while (0)
; #define PG8_MMA(ai, bj, At, Bt) do { __builtin_amdgcn_s_setprio(1); _Pragma("unroll") for (int m = 0; m < 4; ++m) _Pragma("unroll") for (int n = 0; n < 2; ++n) _Pragma("unroll") for (int k = 0; k < 2; ++k) \
;         acc[ai][bj][m][n] = __builtin_amdgcn_mfma_f32_16x16x32_bf16(Bt[n][k], At[m][k], acc[ai][bj][m][n], 0, 0, 0); __builtin_amdgcn_s_setprio(0); } while (0)
; #define PG8_WAIT_V(n) asm volatile("s_waitcnt vmcnt(" #n ")" ::: "memory")
; #define PG8_WAIT_L(n) asm volatile("s_waitcnt lgkmcnt(" #n ")" ::: "memory")
; #define PG8_BAR __builtin_amdgcn_s_barrier()
; #define PG8_SCHED __builtin_amdgcn_sched_barrier(0)
; template <class Epi, class Sched, bool ALIGN_EPI = false, bool SP2 = false>
; __device__ __forceinline__ void gemm_phase(PG8_LAS unsigned char* lds, const Gemm g, const Sched& S, const Epi& E, const int tid_in) {
;     ...
;         for (int t = 0; t < nt; t += 2) {
;             const bool last = (t == nt - 2);
;     ...
;             PG8_LDA(At, 1, 1); PG8_STAGE(PG8_SB(1, 0), b3, voffB); PG8_STAGE(PG8_SB(1, 1), b3 + hstep, voffB); PG8_STAGE(PG8_SA(1, 0), a3, voffA);
;             PG8_WAIT_V(8); PG8_WAIT_L(0); PG8_BAR; PG8_MMA(1, 0, At, B0); PG8_MMA(1, 1, At, B1); PG8_BAR; PG8_SCHED;
	s_add_i32 s12, s52, s17
	v_lshl_add_u64 v[214:215], v[214:215], 0, s[28:29]
	s_mov_b32 m0, s12
	ds_read_b128 v[158:161], v249 offset:49152
	ds_read_b128 v[162:165], v249 offset:50176
	ds_read_b128 v[170:173], v249 offset:51200
	ds_read_b128 v[178:181], v249 offset:52224
	ds_read_b128 v[182:185], v249 offset:53248
	ds_read_b128 v[186:189], v249 offset:54272
	ds_read_b128 v[190:193], v249 offset:55296
	ds_read_b128 v[210:213], v249 offset:56320
	global_load_lds_dwordx4 v[214:215], off
	v_lshl_add_u64 v[214:215], v[216:217], 0, s[28:29]
	s_add_i32 m0, s12, 0x2000
	s_add_i32 s12, s53, s17
	global_load_lds_dwordx4 v[214:215], off
	v_lshl_add_u64 v[214:215], v[218:219], 0, s[28:29]
	s_mov_b32 m0, s12
	s_nop 0
	global_load_lds_dwordx4 v[214:215], off
	v_lshl_add_u64 v[214:215], v[220:221], 0, s[28:29]
	s_add_i32 m0, s12, 0x2000
	s_nop 0
	global_load_lds_dwordx4 v[214:215], off
	v_lshl_add_u64 v[214:215], v[222:223], 0, s[28:29]
	s_mov_b32 m0, s26
	s_nop 0
	global_load_lds_dwordx4 v[214:215], off
	v_lshl_add_u64 v[214:215], v[224:225], 0, s[28:29]
	s_mov_b32 m0, s27
	s_nop 0
	global_load_lds_dwordx4 v[214:215], off
	s_waitcnt vmcnt(8)
	s_waitcnt lgkmcnt(0)
	s_barrier
	v_mfma_f32_16x16x32_bf16 v[66:69], v[126:129], v[158:161], v[66:69]
	v_mfma_f32_16x16x32_bf16 v[66:69], v[130:133], v[162:165], v[66:69]
	v_mfma_f32_16x16x32_bf16 v[50:53], v[126:129], v[170:173], v[50:53]
	v_mfma_f32_16x16x32_bf16 v[50:53], v[130:133], v[178:181], v[50:53]
	v_mfma_f32_16x16x32_bf16 v[34:37], v[126:129], v[182:185], v[34:37]
	v_mfma_f32_16x16x32_bf16 v[34:37], v[130:133], v[186:189], v[34:37]
	v_mfma_f32_16x16x32_bf16 v[18:21], v[126:129], v[190:193], v[18:21]
	v_mfma_f32_16x16x32_bf16 v[18:21], v[130:133], v[210:213], v[18:21]
	v_mfma_f32_16x16x32_bf16 v[62:65], v[134:137], v[158:161], v[62:65]
	v_mfma_f32_16x16x32_bf16 v[62:65], v[138:141], v[162:165], v[62:65]
	v_mfma_f32_16x16x32_bf16 v[46:49], v[134:137], v[170:173], v[46:49]
	v_mfma_f32_16x16x32_bf16 v[46:49], v[138:141], v[178:181], v[46:49]
	v_mfma_f32_16x16x32_bf16 v[30:33], v[134:137], v[182:185], v[30:33]
	v_mfma_f32_16x16x32_bf16 v[30:33], v[138:141], v[186:189], v[30:33]
	v_mfma_f32_16x16x32_bf16 v[14:17], v[134:137], v[190:193], v[14:17]
	v_mfma_f32_16x16x32_bf16 v[14:17], v[138:141], v[210:213], v[14:17]
	v_mfma_f32_16x16x32_bf16 v[58:61], v[142:145], v[158:161], v[58:61]
	v_mfma_f32_16x16x32_bf16 v[58:61], v[146:149], v[162:165], v[58:61]
	v_mfma_f32_16x16x32_bf16 v[42:45], v[142:145], v[170:173], v[42:45]
	v_mfma_f32_16x16x32_bf16 v[42:45], v[146:149], v[178:181], v[42:45]
	v_mfma_f32_16x16x32_bf16 v[26:29], v[142:145], v[182:185], v[26:29]
	v_mfma_f32_16x16x32_bf16 v[26:29], v[146:149], v[186:189], v[26:29]
	v_mfma_f32_16x16x32_bf16 v[10:13], v[142:145], v[190:193], v[10:13]
	v_mfma_f32_16x16x32_bf16 v[10:13], v[146:149], v[210:213], v[10:13]
	v_mfma_f32_16x16x32_bf16 v[54:57], v[150:153], v[158:161], v[54:57]
	v_mfma_f32_16x16x32_bf16 v[54:57], v[154:157], v[162:165], v[54:57]
	v_mfma_f32_16x16x32_bf16 v[38:41], v[150:153], v[170:173], v[38:41]
	v_mfma_f32_16x16x32_bf16 v[38:41], v[154:157], v[178:181], v[38:41]
	v_mfma_f32_16x16x32_bf16 v[22:25], v[150:153], v[182:185], v[22:25]
	v_mfma_f32_16x16x32_bf16 v[22:25], v[154:157], v[186:189], v[22:25]
	v_mfma_f32_16x16x32_bf16 v[6:9], v[150:153], v[190:193], v[6:9]
	v_mfma_f32_16x16x32_bf16 v[6:9], v[154:157], v[210:213], v[6:9]
	s_barrier
	s_add_u32 s10, s10, 0x100
	s_addc_u32 s11, s11, 0
	s_add_u32 s14, s14, 0x100
	s_addc_u32 s15, s15, 0
	s_cmp_ge_u32 s51, s30
	s_mov_b32 s12, s51
